# GLA LDS transposes: adjacent-key lanes exchange via DPP row_ror and write packed 32-bit words (half the bank-conflicted 16-bit LDS writes) for V^T in gla1/gla3 and K^T in gla1
# baseline (speedup 1.0000x reference)
; DI int lane_asm() { int l_; asm volatile("v_mbcnt_lo_u32_b32 %0, -1, 0\n\tv_mbcnt_hi_u32_b32 %0, -1, %0" : "=v"(l_)); return l_; }
; DI void phase_gla1(ArgsP a, int tb_, int l, char* shm, int vcu, int G) {
;     int tid_ = tb_ + lane_asm(); asm volatile("" : "+v"(tid_)); const int tid = tid_, lane = tid & 63, r32 = lane & 31, hi = lane >> 5, wid = tid >> 6;
;     const bf16_t* zr = (const bf16_t*)(a->ws + A_ZR); bf16_t* ST = (bf16_t*)(a->ws + A_ST); float* DEC = (float*)(a->ws + A_DEC);
;     float* LA = (float*)shm; char* KT = shm + 16640; char* VT = shm + 25856;
;     for (int scan = vcu >> 2; scan < 64; scan += (G >> 2)) {
;         const int dir = scan & 1, h = (scan >> 1) & 3, b = scan >> 3;
;         const float* wa2 = a->in[I_WA2] + ((size_t)l * 2 + dir) * 16 * 256 + h * 64; const float* ba2 = a->in[I_BA2] + ((size_t)l * 2 + dir) * 256 + h * 64;
;         const int jb = (wid >> 1) & 1, kb = wid & 1;
;         const bf16x8 wfr = gla_wfrag(wa2, kb * 32 + r32, hi); const float bias = ba2[kb * 32 + r32];
;         const int j = tid >> 3, kg = tid & 7, jl = dir ? 0 : 63;
.LBB0_1255:
	s_or_b64 exec, exec, s[8:9]
	s_ashr_i32 s4, s5, 2
	s_lshl_b32 s34, s26, 1
	v_mbcnt_lo_u32_b32 v0, -1, 0
	v_mbcnt_hi_u32_b32 v0, -1, v0
	s_cmp_gt_i32 s4, 63
	v_add_u32_e32 v0, s1, v0
	s_cbranch_scc1 .LBB0_1268
	s_load_dwordx2 s[22:23], s[6:7], 0xf0
	s_load_dwordx4 s[28:31], s[6:7], 0xa0
	s_ashr_i32 s46, s2, 2
	v_ashrrev_i32_e32 v5, 6, v0
	v_ashrrev_i32_e32 v64, 3, v0
	s_movk_i32 s2, 0xffe0
	v_lshlrev_b32_e32 v9, 5, v5
	v_lshrrev_b32_e32 v6, 2, v0
	v_bfi_b32 v11, s2, v64, v0
	s_movk_i32 s0, 0x90
	s_and_b32 s5, s5, 3
	v_and_b32_e32 v1, 31, v0
	v_and_b32_e32 v14, 32, v9
	v_and_b32_e32 v16, 32, v6
	v_cmp_gt_i32_e64 s[6:7], 4, v5
	v_and_b32_e32 v5, 3, v5
	v_mul_lo_u32 v11, v11, s0
	s_lshl_b32 s27, s5, 6
	v_lshlrev_b32_e32 v3, 2, v1
	v_or_b32_e32 v2, v14, v1
	v_or_b32_e32 v65, v16, v1
	v_add_u32_e32 v18, 0, v11
	v_lshl_or_b32 v11, v5, 5, v1
	v_lshlrev_b32_e32 v1, 7, v1
	s_xor_b32 s35, s27, 0xc0
	v_lshl_or_b32 v12, v5, 12, v1
	v_lshlrev_b32_e32 v1, 2, v14
	v_and_b32_e32 v53, 63, v0
	s_waitcnt lgkmcnt(0)
	s_add_u32 s36, s22, 0xe800000
	v_bfe_u32 v7, v0, 5, 1
	v_and_b32_e32 v15, 7, v0
	v_and_b32_e32 v10, 0xffffffe0, v64
	v_mov_b32_e32 v13, v189
	v_add3_u32 v3, 0, v3, v1
	v_ashrrev_i32_e32 v1, 31, v0
	s_addc_u32 s37, s23, 0
	v_lshlrev_b32_e32 v6, 3, v15
	v_bitop3_b32 v66, v0, 63, v0 bitop3:0xc
	v_add_u32_e32 v67, 0, v9
	v_lshlrev_b32_e32 v9, 2, v53
	v_cmp_lt_i32_e64 s[20:21], 63, v0
	v_lshl_add_u32 v74, v0, 2, 0
	v_mad_u32_u24 v20, v11, s0, 0
	v_lshl_add_u64 v[12:13], s[22:23], 0, v[12:13]
	v_ashrrev_i32_e32 v11, 31, v10
	v_lshl_or_b32 v5, v7, 2, v16
	v_lshl_add_u64 v[0:1], v[0:1], 2, s[22:23]
	s_mov_b64 s[22:23], 0x1e700000
	v_lshl_add_u32 v52, v15, 5, 0
	s_movk_i32 s0, 0x104
	v_lshlrev_b32_e32 v188, 3, v7
	v_add_u32_e32 v68, -4, v9
	v_add_u32_e32 v69, -8, v9
	v_add_u32_e32 v70, -16, v9
	v_subrev_u32_e32 v71, 32, v9
	v_subrev_u32_e32 v72, 64, v9
	v_add_u32_e32 v73, 0xffffff80, v9
	v_lshlrev_b32_e32 v9, 1, v64
	v_lshl_add_u64 v[10:11], v[10:11], 1, v[12:13]
	v_lshl_add_u64 v[50:51], v[0:1], 0, s[22:23]
	v_mul_u32_u24_e32 v0, 0x104, v5
	v_mad_u64_u32 v[54:55], s[22:23], v64, s0, v[52:53]
	v_or_b32_e32 v5, 1, v6
	s_movk_i32 s0, 0x900
	v_lshlrev_b32_e32 v4, 11, v7
	v_lshlrev_b32_e32 v8, 4, v15
	v_add_u32_e32 v17, 0, v9
	v_lshlrev_b32_e32 v19, 4, v7
	v_lshl_add_u64 v[10:11], v[10:11], 0, v[188:189]
	s_mov_b64 s[24:25], 0x1a300000
	v_mul_u32_u24_e32 v1, 0x480, v15
	v_mul_u32_u24_e32 v5, 0x90, v5
	v_mad_u32_u24 v7, v15, s0, 0
	v_cmp_eq_u32_e64 s[8:9], 0, v53
	v_cmp_gt_u32_e64 s[10:11], 2, v53
	v_cmp_gt_u32_e64 s[12:13], 4, v53
	v_cmp_gt_u32_e64 s[14:15], 8, v53
	v_cmp_gt_u32_e64 s[16:17], 16, v53
	v_cmp_gt_u32_e64 s[18:19], 32, v53
	v_lshl_add_u64 v[48:49], v[10:11], 0, s[24:25]
	s_xor_b32 s47, s5, 63
	s_mul_i32 s48, s4, 0x44
	v_lshlrev_b32_e32 v56, 2, v4
	v_lshlrev_b32_e32 v58, 2, v2
	v_lshlrev_b32_e32 v188, 1, v188
	v_lshlrev_b32_e32 v60, 1, v6
	v_lshlrev_b32_e32 v62, 1, v8
	v_add_u32_e32 v55, v3, v0
	v_add_u32_e32 v75, v17, v1
	v_bfe_u32 v93, v75, 1, 1
	v_mov_b32_e32 v94, 0x8e
	v_mad_u32_u24 v92, v93, v94, v75
	v_add_u32_e32 v76, v17, v5
	v_add_u32_e32 v77, v7, v9
	v_bfe_u32 v81, v77, 1, 1
	v_mov_b32_e32 v84, 0x8e
	v_mad_u32_u24 v82, v81, v84, v77
	v_mov_b32_e32 v84, 0xfdfe0606
	v_mul_lo_u32 v83, v81, v84
	v_add_u32_e32 v83, 0x5040100, v83
	v_add_u32_e32 v78, v18, v19
	v_add_u32_e32 v79, v20, v19
	s_branch .LBB0_1258

; DI void phase_gla1(ArgsP a, int tb_, int l, char* shm, int vcu, int G) {
;     ...
;             __syncthreads();
; #pragma unroll
;             for (int i = 0; i < 8; ++i) { const int kd = wid * 8 + i, jj = dir ? 63 - lane : lane; const float x = scan64(LA[jj * 65 + kd], lane); LA[jj * 65 + kd] = x; }
;             __syncthreads();
.LBB0_1264:
	s_or_b64 exec, exec, s[44:45]
	s_waitcnt lgkmcnt(0)
	s_barrier
	ds_read2_b32 v[0:1], v59 offset0:2 offset1:3
	ds_read2_b32 v[2:3], v59 offset1:1
	v_add_u32_e32 v12, s49, v52
	v_lshlrev_b32_e32 v8, 16, v46
	v_and_b32_e32 v9, 0xffff0000, v46
	s_waitcnt lgkmcnt(0)
	v_add_f32_dpp v0, v0, v0 row_shr:1 row_mask:0xf bank_mask:0xf bound_ctrl:1
	v_add_f32_dpp v1, v1, v1 row_shr:1 row_mask:0xf bank_mask:0xf bound_ctrl:1
	v_add_f32_dpp v2, v2, v2 row_shr:1 row_mask:0xf bank_mask:0xf bound_ctrl:1
	v_add_f32_dpp v3, v3, v3 row_shr:1 row_mask:0xf bank_mask:0xf bound_ctrl:1
	v_add_f32_dpp v0, v0, v0 row_shr:2 row_mask:0xf bank_mask:0xf bound_ctrl:1
	v_add_f32_dpp v1, v1, v1 row_shr:2 row_mask:0xf bank_mask:0xf bound_ctrl:1
	v_add_f32_dpp v2, v2, v2 row_shr:2 row_mask:0xf bank_mask:0xf bound_ctrl:1
	v_add_f32_dpp v3, v3, v3 row_shr:2 row_mask:0xf bank_mask:0xf bound_ctrl:1
	v_add_f32_dpp v0, v0, v0 row_shr:4 row_mask:0xf bank_mask:0xf bound_ctrl:1
	v_add_f32_dpp v1, v1, v1 row_shr:4 row_mask:0xf bank_mask:0xf bound_ctrl:1
	v_add_f32_dpp v2, v2, v2 row_shr:4 row_mask:0xf bank_mask:0xf bound_ctrl:1
	v_add_f32_dpp v3, v3, v3 row_shr:4 row_mask:0xf bank_mask:0xf bound_ctrl:1
	v_add_f32_dpp v0, v0, v0 row_shr:8 row_mask:0xf bank_mask:0xf bound_ctrl:1
	v_add_f32_dpp v1, v1, v1 row_shr:8 row_mask:0xf bank_mask:0xf bound_ctrl:1
	v_add_f32_dpp v2, v2, v2 row_shr:8 row_mask:0xf bank_mask:0xf bound_ctrl:1
	v_add_f32_dpp v3, v3, v3 row_shr:8 row_mask:0xf bank_mask:0xf bound_ctrl:1
	v_add_f32_dpp v0, v0, v0 row_bcast:15 row_mask:0xa bank_mask:0xf
	v_add_f32_dpp v1, v1, v1 row_bcast:15 row_mask:0xa bank_mask:0xf
	v_add_f32_dpp v2, v2, v2 row_bcast:15 row_mask:0xa bank_mask:0xf
	v_add_f32_dpp v3, v3, v3 row_bcast:15 row_mask:0xa bank_mask:0xf
	v_add_f32_dpp v0, v0, v0 row_bcast:31 row_mask:0xc bank_mask:0xf
	v_add_f32_dpp v1, v1, v1 row_bcast:31 row_mask:0xc bank_mask:0xf
	v_add_f32_dpp v2, v2, v2 row_bcast:31 row_mask:0xc bank_mask:0xf
	v_add_f32_dpp v3, v3, v3 row_bcast:31 row_mask:0xc bank_mask:0xf
	v_lshlrev_b32_e32 v10, 16, v47
	v_and_b32_e32 v11, 0xffff0000, v47
	s_add_i32 s24, s48, s54
	ds_write2_b32 v59, v2, v3 offset1:1
	ds_write2_b32 v59, v0, v1 offset0:2 offset1:3
	ds_read2_b32 v[0:1], v59 offset0:6 offset1:7
	ds_read2_b32 v[2:3], v59 offset0:4 offset1:5
	s_waitcnt lgkmcnt(0)
	v_add_f32_dpp v0, v0, v0 row_shr:1 row_mask:0xf bank_mask:0xf bound_ctrl:1
	v_add_f32_dpp v1, v1, v1 row_shr:1 row_mask:0xf bank_mask:0xf bound_ctrl:1
	v_add_f32_dpp v2, v2, v2 row_shr:1 row_mask:0xf bank_mask:0xf bound_ctrl:1
	v_add_f32_dpp v3, v3, v3 row_shr:1 row_mask:0xf bank_mask:0xf bound_ctrl:1
	v_add_f32_dpp v0, v0, v0 row_shr:2 row_mask:0xf bank_mask:0xf bound_ctrl:1
	v_add_f32_dpp v1, v1, v1 row_shr:2 row_mask:0xf bank_mask:0xf bound_ctrl:1
	v_add_f32_dpp v2, v2, v2 row_shr:2 row_mask:0xf bank_mask:0xf bound_ctrl:1
	v_add_f32_dpp v3, v3, v3 row_shr:2 row_mask:0xf bank_mask:0xf bound_ctrl:1
	v_add_f32_dpp v0, v0, v0 row_shr:4 row_mask:0xf bank_mask:0xf bound_ctrl:1
	v_add_f32_dpp v1, v1, v1 row_shr:4 row_mask:0xf bank_mask:0xf bound_ctrl:1
	v_add_f32_dpp v2, v2, v2 row_shr:4 row_mask:0xf bank_mask:0xf bound_ctrl:1
	v_add_f32_dpp v3, v3, v3 row_shr:4 row_mask:0xf bank_mask:0xf bound_ctrl:1
	v_add_f32_dpp v0, v0, v0 row_shr:8 row_mask:0xf bank_mask:0xf bound_ctrl:1
	v_add_f32_dpp v1, v1, v1 row_shr:8 row_mask:0xf bank_mask:0xf bound_ctrl:1
	v_add_f32_dpp v2, v2, v2 row_shr:8 row_mask:0xf bank_mask:0xf bound_ctrl:1
	v_add_f32_dpp v3, v3, v3 row_shr:8 row_mask:0xf bank_mask:0xf bound_ctrl:1
	v_add_f32_dpp v0, v0, v0 row_bcast:15 row_mask:0xa bank_mask:0xf
	v_add_f32_dpp v1, v1, v1 row_bcast:15 row_mask:0xa bank_mask:0xf
	v_add_f32_dpp v2, v2, v2 row_bcast:15 row_mask:0xa bank_mask:0xf
	v_add_f32_dpp v3, v3, v3 row_bcast:15 row_mask:0xa bank_mask:0xf
	v_add_f32_dpp v0, v0, v0 row_bcast:31 row_mask:0xc bank_mask:0xf
	v_add_f32_dpp v1, v1, v1 row_bcast:31 row_mask:0xc bank_mask:0xf
	v_add_f32_dpp v2, v2, v2 row_bcast:31 row_mask:0xc bank_mask:0xf
	v_add_f32_dpp v3, v3, v3 row_bcast:31 row_mask:0xc bank_mask:0xf
	ds_write2_b32 v59, v2, v3 offset0:4 offset1:5
	ds_write2_b32 v59, v0, v1 offset0:6 offset1:7
	s_waitcnt lgkmcnt(0)
	s_barrier
; DI float bflo(unsigned u) { return __uint_as_float(u << 16); }
; DI float bfhi(unsigned u) { return __uint_as_float(u & 0xffff0000u); }
; DI bf16_t f2bf(float f) { return (bf16_t)(cvtpk(f, f) & 0xffffu); }
; DI void phase_gla1(ArgsP a, int tb_, int l, char* shm, int vcu, int G) {
;     ...
;             { const float kv[8] = {bflo(kw.x), bfhi(kw.x), bflo(kw.y), bfhi(kw.y), bflo(kw.z), bfhi(kw.z), bflo(kw.w), bfhi(kw.w)};
; #pragma unroll
;               for (int kk = 0; kk < 8; ++kk) { const int kd = kg * 8 + kk; *(bf16_t*)(KT + kd * 144 + j * 2) = f2bf(kv[kk] * __expf(LA[jl * 65 + kd] - LA[j * 65 + kd])); }
;               const unsigned vv[8] = {v0.x, v0.y, v0.z, v0.w, v1.x, v1.y, v1.z, v1.w};
; #pragma unroll
;               for (int q = 0; q < 8; ++q) { *(bf16_t*)(VT + (kg * 16 + 2 * q) * 144 + j * 2) = (bf16_t)(vv[q] & 0xffffu); *(bf16_t*)(VT + (kg * 16 + 2 * q + 1) * 144 + j * 2) = (bf16_t)(vv[q] >> 16); } }
;             if (tid < 64) DEC[(size_t)item * 64 + tid] = __expf(LA[jl * 65 + tid]);
	ds_read2_b32 v[0:1], v12 offset1:1
	ds_read2_b32 v[2:3], v54 offset1:1
	v_lshlrev_b32_e32 v4, 16, v44
	v_and_b32_e32 v5, 0xffff0000, v44
	v_lshlrev_b32_e32 v6, 16, v45
	v_and_b32_e32 v7, 0xffff0000, v45
	s_waitcnt lgkmcnt(0)
	v_sub_f32_e32 v0, v0, v2
	v_sub_f32_e32 v1, v1, v3
	v_mul_f32_e32 v0, 0x3fb8aa3b, v0
	v_mul_f32_e32 v1, 0x3fb8aa3b, v1
	v_exp_f32_e32 v0, v0
	v_exp_f32_e32 v1, v1
	s_nop 0
	v_mul_f32_e32 v0, v0, v4
	v_mul_f32_e32 v1, v1, v5
	v_cvt_pk_bf16_f32 v89, v0, v1
	s_nop 1
	v_mov_b32_dpp v90, v89 row_ror:8 row_mask:0xf bank_mask:0xf
	v_perm_b32 v91, v90, v89, v83
	ds_write_b32 v92, v91 offset:16640
	ds_read2_b32 v[0:1], v12 offset0:2 offset1:3
	ds_read2_b32 v[2:3], v54 offset0:2 offset1:3
	s_waitcnt lgkmcnt(0)
	v_sub_f32_e32 v0, v0, v2
	v_sub_f32_e32 v1, v1, v3
	v_mul_f32_e32 v0, 0x3fb8aa3b, v0
	v_mul_f32_e32 v1, 0x3fb8aa3b, v1
	v_exp_f32_e32 v0, v0
	v_exp_f32_e32 v1, v1
	s_nop 0
	v_mul_f32_e32 v0, v0, v6
	v_mul_f32_e32 v1, v1, v7
	v_cvt_pk_bf16_f32 v89, v0, v1
	s_nop 1
	v_mov_b32_dpp v90, v89 row_ror:8 row_mask:0xf bank_mask:0xf
	v_perm_b32 v91, v90, v89, v83
	ds_write_b32 v92, v91 offset:16928
	ds_read2_b32 v[0:1], v12 offset0:4 offset1:5
	ds_read2_b32 v[2:3], v54 offset0:4 offset1:5
	s_waitcnt lgkmcnt(0)
	v_sub_f32_e32 v0, v0, v2
	v_sub_f32_e32 v1, v1, v3
	v_mul_f32_e32 v0, 0x3fb8aa3b, v0
	v_mul_f32_e32 v1, 0x3fb8aa3b, v1
	v_exp_f32_e32 v0, v0
	v_exp_f32_e32 v1, v1
	s_nop 0
	v_mul_f32_e32 v0, v0, v8
	v_mul_f32_e32 v1, v1, v9
	v_cvt_pk_bf16_f32 v89, v0, v1
	s_nop 1
	v_mov_b32_dpp v90, v89 row_ror:8 row_mask:0xf bank_mask:0xf
	v_perm_b32 v91, v90, v89, v83
	ds_write_b32 v92, v91 offset:17216
	ds_read2_b32 v[0:1], v12 offset0:6 offset1:7
	ds_read2_b32 v[2:3], v54 offset0:6 offset1:7
	s_waitcnt lgkmcnt(0)
	v_sub_f32_e32 v0, v0, v2
	v_sub_f32_e32 v1, v1, v3
	v_mul_f32_e32 v0, 0x3fb8aa3b, v0
	v_mul_f32_e32 v1, 0x3fb8aa3b, v1
	v_exp_f32_e32 v0, v0
	v_exp_f32_e32 v1, v1
	s_nop 0
	v_mul_f32_e32 v0, v0, v10
	v_mul_f32_e32 v1, v1, v11
	v_cvt_pk_bf16_f32 v89, v0, v1
	s_nop 1
	v_mov_b32_dpp v90, v89 row_ror:8 row_mask:0xf bank_mask:0xf
	v_perm_b32 v91, v90, v89, v83
	ds_write_b32 v92, v91 offset:17504
	v_mov_b32_dpp v85, v24 row_ror:8 row_mask:0xf bank_mask:0xf
	v_perm_b32 v86, v85, v24, v83
	ds_write_b32 v82, v86 offset:25856
	v_mov_b32_dpp v87, v25 row_ror:8 row_mask:0xf bank_mask:0xf
	v_perm_b32 v88, v87, v25, v83
	ds_write_b32 v82, v88 offset:26144
	v_mov_b32_dpp v85, v26 row_ror:8 row_mask:0xf bank_mask:0xf
	v_perm_b32 v86, v85, v26, v83
	ds_write_b32 v82, v86 offset:26432
	v_mov_b32_dpp v87, v27 row_ror:8 row_mask:0xf bank_mask:0xf
	v_perm_b32 v88, v87, v27, v83
	ds_write_b32 v82, v88 offset:26720
	v_mov_b32_dpp v85, v20 row_ror:8 row_mask:0xf bank_mask:0xf
	v_perm_b32 v86, v85, v20, v83
	ds_write_b32 v82, v86 offset:27008
	v_mov_b32_dpp v87, v21 row_ror:8 row_mask:0xf bank_mask:0xf
	v_perm_b32 v88, v87, v21, v83
	ds_write_b32 v82, v88 offset:27296
	v_mov_b32_dpp v85, v22 row_ror:8 row_mask:0xf bank_mask:0xf
	v_perm_b32 v86, v85, v22, v83
	ds_write_b32 v82, v86 offset:27584
	v_mov_b32_dpp v87, v23 row_ror:8 row_mask:0xf bank_mask:0xf
	v_perm_b32 v88, v87, v23, v83
	ds_write_b32 v82, v88 offset:27872
	s_and_saveexec_b64 s[44:45], s[20:21]
	s_xor_b64 s[44:45], exec, s[44:45]
	s_ashr_i32 s25, s24, 31
	s_or_saveexec_b64 s[44:45], s[44:45]
	v_mov_b64_e32 v[20:21], s[24:25]
	s_xor_b64 exec, exec, s[44:45]
	s_cbranch_execz .LBB0_1259
	ds_read_b32 v0, v80
	s_ashr_i32 s25, s24, 31
	s_lshl_b64 s[60:61], s[24:25], 8
	v_mov_b64_e32 v[20:21], s[24:25]
	s_waitcnt lgkmcnt(0)
	v_mul_f32_e32 v0, 0x3fb8aa3b, v0
	v_exp_f32_e32 v2, v0
	v_lshl_add_u64 v[0:1], v[50:51], 0, s[60:61]
	global_store_dword v[0:1], v2, off
	s_branch .LBB0_1259

; DI int lane_asm() { int l_; asm volatile("v_mbcnt_lo_u32_b32 %0, -1, 0\n\tv_mbcnt_hi_u32_b32 %0, -1, %0" : "=v"(l_)); return l_; }
; DI void phase_gla3(ArgsP a, int tb_, int l, bool with_ctx, char* shm, int vcu, int G) {
;     int tid_ = tb_ + lane_asm(); asm volatile("" : "+v"(tid_)); const int tid = tid_, lane = tid & 63, r32 = lane & 31, hi = lane >> 5, wid = tid >> 6;
;     const bf16_t* zr = (const bf16_t*)(a->ws + A_ZR); const bf16_t* ST = (const bf16_t*)(a->ws + A_ST); bf16_t* og = (bf16_t*)(a->ws + A_OG);
;     float* LA = (float*)shm; char* QT = shm + 33792; char* KTt = shm + 52224; char* VT = shm + 70656; char* AM = shm + 89088; float* OS = (float*)shm;
;     const float* ggl = a->in[I_GGLA] + l * 128;
;     for (int bh = vcu >> 3; bh < 32; bh += (G >> 3)) {
;         const int h = bh & 3, b = bh >> 2;
;         const int ldir = wid >> 2, ljb = (wid >> 1) & 1, lkb = wid & 1;
;         const float* wa2 = a->in[I_WA2] + ((size_t)l * 2 + ldir) * 16 * 256 + h * 64; const float* ba2 = a->in[I_BA2] + ((size_t)l * 2 + ldir) * 256 + h * 64;
;         const bf16x8 wfr = gla_wfrag(wa2, lkb * 32 + r32, hi); const float bias = ba2[lkb * 32 + r32];
;         const int j = tid >> 3, kg = tid & 7;
;     ...
;         int pst = vcu & 7; if (pst < 4 && !with_ctx) pst += 8;
;         bf16x8 ngfr; u32x4 nqw, nkw, nv0, nv1;
;         GLA3_LOAD(pst, ngfr, nqw, nkw, nv0, nv1);
.LBB0_1413:
	s_mov_b64 s[6:7], s[64:65]
	s_ashr_i32 s5, s2, 3
	v_mbcnt_lo_u32_b32 v0, -1, 0
	v_mbcnt_hi_u32_b32 v0, -1, v0
	s_cmp_gt_i32 s5, 31
	v_add_u32_e32 v0, s1, v0
	s_cbranch_scc1 .LBB0_1421
	s_and_b32 s2, s2, 7
	s_cmp_gt_u32 s2, 3
	s_cselect_b64 s[8:9], -1, 0
	s_or_b64 s[8:9], s[68:69], s[8:9]
	s_or_b32 s10, s2, 8
	s_and_b64 s[8:9], s[8:9], exec
	s_load_dwordx2 s[54:55], s[6:7], 0xf0
	s_cselect_b32 s85, s2, s10
	s_load_dwordx4 s[8:11], s[6:7], 0xa0
	s_nop 0
	s_load_dwordx2 s[6:7], s[6:7], 0xb0
	v_ashrrev_i32_e32 v2, 8, v0
	s_cmp_lt_u32 s85, 4
	s_mov_b32 s35, s81
	v_ashrrev_i32_e32 v1, 6, v0
	v_ashrrev_i32_e32 v3, 31, v2
	s_cselect_b64 s[82:83], -1, 0
	s_lshl_b32 s2, s85, 6
	v_lshl_add_u64 v[4:5], v[2:3], 0, s[34:35]
	v_lshlrev_b32_e32 v3, 5, v1
	s_add_i32 s71, s2, 0xffffff00
	s_or_b32 s75, s2, 0x8000
	v_and_b32_e32 v10, 31, v0
	v_bfe_u32 v13, v0, 5, 1
	v_lshlrev_b64 v[6:7], 14, v[4:5]
	v_and_b32_e32 v3, 32, v3
	s_waitcnt lgkmcnt(0)
	s_add_u32 s68, s54, 0xe800000
	v_lshl_add_u64 v[6:7], s[8:9], 0, v[6:7]
	v_lshlrev_b64 v[4:5], 10, v[4:5]
	v_or_b32_e32 v14, v3, v10
	v_lshlrev_b32_e32 v188, 13, v13
	s_addc_u32 s69, s55, 0
	s_lshl_b32 s80, s26, 7
	v_lshl_add_u64 v[4:5], s[10:11], 0, v[4:5]
	v_lshl_add_u64 v[6:7], v[6:7], 0, v[188:189]
	v_lshlrev_b32_e32 v188, 2, v14
	s_lshl_b64 s[12:13], s[80:81], 2
	v_lshl_add_u64 v[58:59], v[4:5], 0, v[188:189]
	v_and_b32_e32 v15, 7, v0
	v_lshrrev_b32_e32 v4, 2, v0
	s_add_u32 s60, s6, s12
	v_and_b32_e32 v16, 32, v4
	v_lshlrev_b32_e32 v4, 5, v15
	v_mov_b32_e32 v5, v189
	s_addc_u32 s61, s7, s13
	v_lshl_add_u64 v[8:9], s[54:55], 0, v[4:5]
	s_mov_b64 s[6:7], 0xc600000
	v_lshl_add_u32 v11, v10, 2, 0
	v_lshl_add_u64 v[56:57], v[6:7], 0, v[188:189]
	v_lshlrev_b32_e32 v62, 3, v13
	v_lshlrev_b32_e32 v3, 2, v3
	v_lshlrev_b32_e32 v188, 4, v13
	v_lshl_add_u64 v[68:69], v[8:9], 0, s[6:7]
	v_lshlrev_b32_e32 v8, 2, v13
	v_mul_i32_i24_e32 v13, 0x4100, v2
	v_and_b32_e32 v12, 63, v0
	v_add3_u32 v13, v11, v3, v13
	v_bitop3_b32 v3, v0, 63, v0 bitop3:0xc
	v_cmp_gt_u32_e32 vcc, s96, v0
	s_movk_i32 s6, 0x4100
	v_ashrrev_i32_e32 v63, 3, v0
	v_cndmask_b32_e32 v3, v3, v12, vcc
	v_or_b32_e32 v65, v16, v10
	v_or_b32_e32 v9, v8, v16
	v_mad_i32_i24 v16, v2, s6, 0
	v_mul_u32_u24_e32 v3, 0x104, v3
	v_and_b32_e32 v0, 0xc0, v0
	v_add3_u32 v67, v16, v3, v0
	v_and_b32_e32 v21, 3, v1
	v_lshlrev_b32_e32 v0, 7, v10
	v_lshl_add_u64 v[6:7], s[54:55], 0, v[188:189]
	s_movk_i32 s18, 0x104
	v_lshl_or_b32 v0, v21, 12, v0
	v_mov_b32_e32 v1, v189
	v_lshlrev_b32_e32 v3, 2, v12
	v_cmp_eq_u32_e64 s[6:7], 0, v12
	v_cmp_gt_u32_e64 s[8:9], 2, v12
	v_cmp_gt_u32_e64 s[10:11], 4, v12
	v_cmp_gt_u32_e64 s[12:13], 8, v12
	v_cmp_gt_u32_e64 s[14:15], 16, v12
	v_cmp_gt_u32_e64 s[16:17], 32, v12
	v_mul_lo_u32 v12, v63, s18
	v_lshl_add_u64 v[6:7], v[6:7], 0, v[0:1]
	s_mov_b64 s[20:21], 0x1a300000
	s_movk_i32 s18, 0x2400
	v_lshl_add_u64 v[70:71], v[6:7], 0, s[20:21]
	v_mul_i32_i24_e32 v1, 0x2400, v2
	v_mad_i32_i24 v6, v2, s18, 0
	v_lshlrev_b32_e32 v22, 1, v14
	v_readlane_b32 s18, v255, 8
	v_lshlrev_b32_e32 v60, 4, v2
	s_movk_i32 s19, 0x90
	v_add3_u32 v22, s18, v1, v22
	v_lshlrev_b32_e32 v1, 5, v2
	v_or_b32_e32 v2, v1, v10
	v_mul_lo_u32 v2, v2, s19
	v_add_u32_e32 v23, s18, v2
	v_readlane_b32 s18, v255, 9
	v_lshl_or_b32 v10, v21, 5, v10
	v_mul_lo_u32 v16, v63, s19
	v_mov_b32_e32 v24, s18
	s_movk_i32 s18, 0x900
	v_mad_u32_u24 v7, v65, s19, v6
	v_mad_u32_u24 v6, v14, s19, v6
	v_mad_u32_u24 v10, v10, s19, v24
	v_mad_u32_u24 v24, v15, s18, v24
	v_cmp_le_u32_e64 s[18:19], v14, v9
	v_add_u32_e32 v25, 0, v2
	v_or_b32_e32 v2, 1, v9
	v_cndmask_b32_e64 v39, 0, 1, s[18:19]
	v_cmp_ge_u32_e64 s[18:19], v14, v9
	v_cmp_le_u32_e64 s[20:21], v14, v2
	v_add_u32_e32 v88, -4, v3
	v_cndmask_b32_e64 v40, 0, 1, s[18:19]
	v_cndmask_b32_e32 v39, v40, v39, vcc
	v_and_b32_e32 v39, 1, v39
	v_cndmask_b32_e64 v2, 0, 1, s[20:21]
	v_cmp_gt_u32_e64 s[20:21], v14, v9
	v_add_u32_e32 v89, -8, v3
	v_add_u32_e32 v90, -16, v3
	v_subrev_u32_e32 v91, 32, v3
	v_subrev_u32_e32 v92, 64, v3
	v_add_u32_e32 v93, 0xffffff80, v3
	v_or_b32_e32 v1, v8, v1
	v_lshl_add_u32 v8, v21, 7, v11
	v_xor_b32_e32 v94, 4, v3
	v_xor_b32_e32 v95, 8, v3
	v_xor_b32_e32 v96, 16, v3
	v_mul_u32_u24_e32 v21, 0x104, v9
	v_or_b32_e32 v3, 2, v9
	v_or_b32_e32 v26, 3, v9
	v_or_b32_e32 v27, 8, v9
	v_or_b32_e32 v28, 9, v9
	v_or_b32_e32 v29, 10, v9
	v_or_b32_e32 v30, 11, v9
	v_or_b32_e32 v31, 16, v9
	v_or_b32_e32 v32, 17, v9
	v_or_b32_e32 v33, 18, v9
	v_or_b32_e32 v34, 19, v9
	v_or_b32_e32 v35, 24, v9
	v_or_b32_e32 v36, 25, v9
	v_or_b32_e32 v37, 26, v9
	v_or_b32_e32 v38, 27, v9
	v_cmp_eq_u32_e64 s[18:19], 1, v39
	v_mul_u32_u24_e32 v39, 0x90, v9
	v_cndmask_b32_e64 v9, 0, 1, s[20:21]
	v_cndmask_b32_e32 v2, v9, v2, vcc
	v_and_b32_e32 v2, 1, v2
	v_cmp_le_u32_e64 s[22:23], v14, v3
	v_cmp_eq_u32_e64 s[20:21], 1, v2
	v_cmp_le_u32_e64 s[24:25], v14, v26
	v_cndmask_b32_e64 v2, 0, 1, s[22:23]
	v_cmp_ge_u32_e64 s[22:23], v14, v3
; DI bf16_t f2bf(float f) { return (bf16_t)(cvtpk(f, f) & 0xffffu); }
; DI int lane_asm() { int l_; asm volatile("v_mbcnt_lo_u32_b32 %0, -1, 0\n\tv_mbcnt_hi_u32_b32 %0, -1, %0" : "=v"(l_)); return l_; }
; DI int crow(int r, int hi) { return (r & 3) + 8 * (r >> 2) + 4 * hi; }
; DI void phase_gla3(ArgsP a, int tb_, int l, bool with_ctx, char* shm, int vcu, int G) {
;     int tid_ = tb_ + lane_asm(); asm volatile("" : "+v"(tid_)); const int tid = tid_, lane = tid & 63, r32 = lane & 31, hi = lane >> 5, wid = tid >> 6;
;     const bf16_t* zr = (const bf16_t*)(a->ws + A_ZR); const bf16_t* ST = (const bf16_t*)(a->ws + A_ST); bf16_t* og = (bf16_t*)(a->ws + A_OG);
;     float* LA = (float*)shm; char* QT = shm + 33792; char* KTt = shm + 52224; char* VT = shm + 70656; char* AM = shm + 89088; float* OS = (float*)shm;
;     const float* ggl = a->in[I_GGLA] + l * 128;
;     for (int bh = vcu >> 3; bh < 32; bh += (G >> 3)) {
;         const int h = bh & 3, b = bh >> 2;
;         const int ldir = wid >> 2, ljb = (wid >> 1) & 1, lkb = wid & 1;
;         const float* wa2 = a->in[I_WA2] + ((size_t)l * 2 + ldir) * 16 * 256 + h * 64; const float* ba2 = a->in[I_BA2] + ((size_t)l * 2 + ldir) * 256 + h * 64;
;         const bf16x8 wfr = gla_wfrag(wa2, lkb * 32 + r32, hi); const float bias = ba2[lkb * 32 + r32];
;         const int j = tid >> 3, kg = tid & 7;
;     ...
;         int pst = vcu & 7; if (pst < 4 && !with_ctx) pst += 8;
;         bf16x8 ngfr; u32x4 nqw, nkw, nv0, nv1;
;         GLA3_LOAD(pst, ngfr, nqw, nkw, nv0, nv1);
;     ...
;               for (int r = 0; r < 16; ++r) { const int ir = ib * 32 + crow(r, hi); const bool keep = dir ? (jc >= ir) : (jc <= ir); *(bf16_t*)(AM + dir * 9216 + ir * 144 + jc * 2) = f2bf(keep ? acc[r] : 0.f); } }
	v_cmp_le_u32_e64 s[26:27], v14, v27
	v_cmp_le_u32_e64 s[28:29], v14, v28
	v_cndmask_b32_e64 v3, 0, 1, s[22:23]
	v_cndmask_b32_e32 v2, v3, v2, vcc
	v_and_b32_e32 v2, 1, v2
	v_cmp_eq_u32_e64 s[22:23], 1, v2
	v_cndmask_b32_e64 v2, 0, 1, s[24:25]
	v_cmp_ge_u32_e64 s[24:25], v14, v26
	v_cmp_le_u32_e64 s[30:31], v14, v29
	v_cmp_le_u32_e64 s[34:35], v14, v30
	v_cndmask_b32_e64 v3, 0, 1, s[24:25]
	v_cndmask_b32_e32 v2, v3, v2, vcc
	v_and_b32_e32 v2, 1, v2
	v_cmp_eq_u32_e64 s[24:25], 1, v2
	v_cndmask_b32_e64 v2, 0, 1, s[26:27]
	v_cmp_ge_u32_e64 s[26:27], v14, v27
	v_cmp_le_u32_e64 s[36:37], v14, v31
	v_cmp_le_u32_e64 s[38:39], v14, v32
	v_cndmask_b32_e64 v3, 0, 1, s[26:27]
	v_cndmask_b32_e32 v2, v3, v2, vcc
	v_and_b32_e32 v2, 1, v2
	v_cmp_eq_u32_e64 s[26:27], 1, v2
	v_cndmask_b32_e64 v2, 0, 1, s[28:29]
	v_cmp_ge_u32_e64 s[28:29], v14, v28
	v_cmp_le_u32_e64 s[40:41], v14, v33
	v_cmp_le_u32_e64 s[42:43], v14, v34
	v_cndmask_b32_e64 v3, 0, 1, s[28:29]
	v_cndmask_b32_e32 v2, v3, v2, vcc
	v_and_b32_e32 v2, 1, v2
	v_cmp_eq_u32_e64 s[28:29], 1, v2
	v_cndmask_b32_e64 v2, 0, 1, s[30:31]
	v_cmp_ge_u32_e64 s[30:31], v14, v29
	v_cmp_le_u32_e64 s[44:45], v14, v35
	v_cmp_le_u32_e64 s[46:47], v14, v36
	v_cndmask_b32_e64 v3, 0, 1, s[30:31]
	v_cndmask_b32_e32 v2, v3, v2, vcc
	v_and_b32_e32 v2, 1, v2
	v_cmp_eq_u32_e64 s[30:31], 1, v2
	v_cndmask_b32_e64 v2, 0, 1, s[34:35]
	v_cmp_ge_u32_e64 s[34:35], v14, v30
	v_cmp_le_u32_e64 s[48:49], v14, v37
	v_cmp_le_u32_e64 s[50:51], v14, v38
	v_cndmask_b32_e64 v3, 0, 1, s[34:35]
	v_cndmask_b32_e32 v2, v3, v2, vcc
	v_and_b32_e32 v2, 1, v2
	v_cmp_eq_u32_e64 s[34:35], 1, v2
	v_cndmask_b32_e64 v2, 0, 1, s[36:37]
	v_cmp_ge_u32_e64 s[36:37], v14, v31
	s_movk_i32 s33, 0x210
	v_lshlrev_b32_e32 v66, 4, v15
	v_cndmask_b32_e64 v3, 0, 1, s[36:37]
	v_cndmask_b32_e32 v2, v3, v2, vcc
	v_and_b32_e32 v2, 1, v2
	v_cmp_eq_u32_e64 s[36:37], 1, v2
	v_cndmask_b32_e64 v2, 0, 1, s[38:39]
	v_cmp_ge_u32_e64 s[38:39], v14, v32
	v_add_u32_e32 v17, 0, v4
	v_mul_lo_u32 v11, v63, s33
	v_cndmask_b32_e64 v3, 0, 1, s[38:39]
	v_cndmask_b32_e32 v2, v3, v2, vcc
	v_and_b32_e32 v2, 1, v2
	v_cmp_eq_u32_e64 s[38:39], 1, v2
	v_cndmask_b32_e64 v2, 0, 1, s[40:41]
	v_cmp_ge_u32_e64 s[40:41], v14, v33
	v_mul_lo_u32 v9, v1, s33
	s_lshl_b32 s33, s85, 14
	v_cndmask_b32_e64 v3, 0, 1, s[40:41]
	v_cndmask_b32_e32 v2, v3, v2, vcc
	v_and_b32_e32 v2, 1, v2
	v_cmp_eq_u32_e64 s[40:41], 1, v2
	v_cndmask_b32_e64 v2, 0, 1, s[42:43]
	v_cmp_ge_u32_e64 s[42:43], v14, v34
	v_sub_u32_e32 v18, v17, v66
	v_or3_b32 v0, s33, v188, v0
	v_cndmask_b32_e64 v3, 0, 1, s[42:43]
	v_cndmask_b32_e32 v2, v3, v2, vcc
	v_and_b32_e32 v2, 1, v2
	v_cmp_eq_u32_e64 s[42:43], 1, v2
	v_cndmask_b32_e64 v2, 0, 1, s[44:45]
	v_cmp_ge_u32_e64 s[44:45], v14, v35
	v_mov_b32_e32 v1, v189
	s_lshl_b32 s96, s5, 1
	v_cndmask_b32_e64 v3, 0, 1, s[44:45]
	v_cndmask_b32_e32 v2, v3, v2, vcc
	v_and_b32_e32 v2, 1, v2
	v_cmp_eq_u32_e64 s[44:45], 1, v2
	v_cndmask_b32_e64 v2, 0, 1, s[46:47]
	v_cmp_ge_u32_e64 s[46:47], v14, v36
	s_lshl_b32 s97, s4, 1
	s_add_i32 s33, s2, 0x100
	v_cndmask_b32_e64 v3, 0, 1, s[46:47]
	v_cndmask_b32_e32 v2, v3, v2, vcc
	v_and_b32_e32 v2, 1, v2
	v_cmp_eq_u32_e64 s[46:47], 1, v2
	v_cndmask_b32_e64 v2, 0, 1, s[48:49]
	v_cmp_ge_u32_e64 s[48:49], v14, v37
	v_mad_u32_u24 v19, v15, 48, v18
	v_lshlrev_b32_e32 v20, 1, v63
	v_cndmask_b32_e64 v3, 0, 1, s[48:49]
	v_cndmask_b32_e32 v2, v3, v2, vcc
	v_and_b32_e32 v2, 1, v2
	v_cmp_eq_u32_e64 s[48:49], 1, v2
	v_cndmask_b32_e64 v2, 0, 1, s[50:51]
	v_cmp_ge_u32_e64 s[50:51], v14, v38
	v_lshl_add_u64 v[0:1], s[54:55], 0, v[0:1]
	s_mov_b64 s[54:55], 0x1a300040
	v_cndmask_b32_e64 v3, 0, 1, s[50:51]
	v_cndmask_b32_e32 v2, v3, v2, vcc
	v_and_b32_e32 v2, 1, v2
	v_cmp_eq_u32_e64 s[50:51], 1, v2
	v_lshlrev_b32_e32 v2, 6, v15
	v_mov_b32_e32 v3, v189
	s_sub_u32 s63, 0, s85
	v_ashrrev_i32_e32 v61, 31, v60
	v_lshlrev_b32_e32 v64, 3, v15
	v_lshl_add_u64 v[72:73], s[60:61], 0, v[2:3]
	global_load_dwordx4 v[192:195], v[72:73], off
	global_load_dwordx4 v[196:199], v[72:73], off offset:16
	global_load_dwordx4 v[200:203], v[72:73], off offset:32
	global_load_dwordx4 v[204:207], v[72:73], off offset:48
	s_waitcnt vmcnt(0)
	v_lshl_add_u64 v[74:75], s[68:69], 0, v[4:5]
	v_lshl_add_u64 v[76:77], v[0:1], 0, s[54:55]
	v_or_b32_e32 v97, s33, v65
	v_add_u32_e32 v98, s2, v63
	s_subb_u32 s52, 0, 0
	s_or_b32 s58, s96, 1
	v_add_u32_e32 v99, v13, v21
	v_add_u32_e32 v100, v17, v12
	v_add_u32_e32 v101, v18, v16
	v_add_u32_e32 v102, v24, v20
	v_bfe_u32 v208, v102, 1, 1
	v_mov_b32_e32 v211, 0x8e
	v_mad_u32_u24 v209, v208, v211, v102
	v_mov_b32_e32 v211, 0xfdfe0606
	v_mul_lo_u32 v210, v208, v211
	v_add_u32_e32 v210, 0x5040100, v210
	v_add_u32_e32 v103, v7, v188
	v_add_u32_e32 v104, v6, v188
	v_add_u32_e32 v105, v22, v39
	v_add_u32_e32 v106, v23, v188
	v_add_u32_e32 v107, v10, v188
	v_add_u32_e32 v108, v25, v188
	v_add_u32_e32 v109, v8, v9
	v_add_u32_e32 v110, v19, v11
	s_branch .LBB0_1416

; DI int crow(int r, int hi) { return (r & 3) + 8 * (r >> 2) + 4 * hi; }
; DI float logsig(float x) { return fminf(x, 0.f) - __logf(1.f + __expf(-fabsf(x))); }
; DI void phase_gla3(ArgsP a, int tb_, int l, bool with_ctx, char* shm, int vcu, int G) {
;     ...
;               acc = __builtin_amdgcn_mfma_f32_32x32x16_bf16(gfr, wfr, acc, 0, 0, 0);
; #pragma unroll
;               for (int r = 0; r < 16; ++r) LA[ldir * 4160 + (ljb * 32 + crow(r, hi)) * 65 + lkb * 32 + r32] = logsig(acc[r] + bias) * (1.f / 16.f); }
.LBB0_1417:
	v_mfma_f32_32x32x16_bf16 v[0:15], v[0:3], v[16:19], 0
	v_lshlrev_b32_e32 v118, 16, v54
	v_and_b32_e32 v119, 0xffff0000, v54
	v_mul_f32_e64 v118, v118, s90
	v_mul_f32_e64 v119, v119, s90
	v_lshlrev_b32_e32 v120, 16, v50
	v_and_b32_e32 v121, 0xffff0000, v50
	v_lshlrev_b32_e32 v54, 16, v55
	v_and_b32_e32 v55, 0xffff0000, v55
	s_nop 3
	v_add_f32_e32 v0, v111, v0
	v_mul_f32_e64 v79, |v0|, s77
	v_exp_f32_e32 v79, v79
	v_add_f32_e32 v1, v111, v1
	v_mul_f32_e64 v81, |v1|, s77
	v_exp_f32_e32 v81, v81
	v_add_f32_e32 v79, 1.0, v79
	v_cmp_gt_f32_e32 vcc, s76, v79
	v_min_f32_e32 v0, 0, v0
	v_add_f32_e32 v81, 1.0, v81
	v_cndmask_b32_e64 v114, 0, 32, vcc
	v_ldexp_f32 v79, v79, v114
	v_log_f32_e32 v79, v79
	v_cmp_gt_f32_e64 s[54:55], s76, v81
	v_cndmask_b32_e32 v114, 0, v240, vcc
	v_add_f32_e32 v2, v111, v2
	v_cndmask_b32_e64 v115, 0, 32, s[54:55]
	v_ldexp_f32 v81, v81, v115
	v_mul_f32_e32 v115, 0x3f317217, v79
	v_log_f32_e32 v81, v81
	v_fma_f32 v115, v79, s62, -v115
	v_fmac_f32_e32 v115, 0x3377d1cf, v79
	v_cmp_lt_f32_e64 vcc, |v79|, s95
	v_fmac_f32_e32 v115, 0x3f317217, v79
	v_mul_f32_e32 v116, 0x3f317217, v81
	v_cndmask_b32_e32 v79, v79, v115, vcc
	v_sub_f32_e32 v79, v79, v114
	v_sub_f32_e32 v0, v0, v79
	v_fma_f32 v79, v81, s62, -v116
	v_fmac_f32_e32 v79, 0x3377d1cf, v81
	v_fmac_f32_e32 v79, 0x3f317217, v81
	v_cmp_lt_f32_e64 vcc, |v81|, s95
	v_cndmask_b32_e64 v114, 0, v240, s[54:55]
	v_min_f32_e32 v1, 0, v1
	v_cndmask_b32_e32 v79, v81, v79, vcc
	v_mul_f32_e64 v81, |v2|, s77
	v_exp_f32_e32 v81, v81
	v_sub_f32_e32 v79, v79, v114
	v_sub_f32_e32 v1, v1, v79
	v_mul_f32_e32 v0, 0x3d800000, v0
	v_add_f32_e32 v79, 1.0, v81
	v_cmp_gt_f32_e32 vcc, s76, v79
	v_mul_f32_e32 v1, 0x3d800000, v1
	ds_write2_b32 v99, v0, v1 offset1:65
	v_cndmask_b32_e64 v81, 0, 32, vcc
	v_ldexp_f32 v79, v79, v81
	v_log_f32_e32 v79, v79
	v_min_f32_e32 v0, 0, v2
	v_add_f32_e32 v2, v111, v3
	v_mul_f32_e64 v3, |v2|, s77
	v_exp_f32_e32 v3, v3
	v_mul_f32_e32 v1, 0x3f317217, v79
	v_fma_f32 v1, v79, s62, -v1
	v_fmac_f32_e32 v1, 0x3377d1cf, v79
	v_fmac_f32_e32 v1, 0x3f317217, v79
	v_cmp_lt_f32_e64 s[54:55], |v79|, s95
	v_add_f32_e32 v3, 1.0, v3
	v_pk_mul_f32 v[54:55], v[54:55], s[90:91] op_sel_hi:[1,0]
	v_cndmask_b32_e64 v1, v79, v1, s[54:55]
	v_cndmask_b32_e32 v79, 0, v240, vcc
	v_cmp_gt_f32_e32 vcc, s76, v3
	v_sub_f32_e32 v1, v1, v79
	v_sub_f32_e32 v0, v0, v1
	v_cndmask_b32_e64 v79, 0, 32, vcc
	v_ldexp_f32 v3, v3, v79
	v_log_f32_e32 v3, v3
	v_min_f32_e32 v1, 0, v2
	v_cndmask_b32_e32 v79, 0, v240, vcc
	v_mul_f32_e32 v0, 0x3d800000, v0
	v_mul_f32_e32 v2, 0x3f317217, v3
	v_fma_f32 v2, v3, s62, -v2
	v_fmac_f32_e32 v2, 0x3377d1cf, v3
	v_fmac_f32_e32 v2, 0x3f317217, v3
	v_cmp_lt_f32_e64 s[54:55], |v3|, s95
	v_lshlrev_b32_e32 v50, 16, v51
	v_and_b32_e32 v51, 0xffff0000, v51
	v_cndmask_b32_e64 v2, v3, v2, s[54:55]
	v_add_f32_e32 v3, v111, v4
	v_mul_f32_e64 v4, |v3|, s77
	v_exp_f32_e32 v4, v4
	v_sub_f32_e32 v2, v2, v79
	v_sub_f32_e32 v1, v1, v2
	v_mul_f32_e32 v1, 0x3d800000, v1
	v_add_f32_e32 v2, 1.0, v4
	v_cmp_gt_f32_e32 vcc, s76, v2
	ds_write2_b32 v99, v0, v1 offset0:130 offset1:195
	v_min_f32_e32 v0, 0, v3
	v_cndmask_b32_e64 v4, 0, 32, vcc
	v_ldexp_f32 v2, v2, v4
	v_log_f32_e32 v2, v2
	v_add_f32_e32 v3, v111, v5
	v_mul_f32_e64 v4, |v3|, s77
	v_exp_f32_e32 v4, v4
	v_mul_f32_e32 v1, 0x3f317217, v2
	v_fma_f32 v1, v2, s62, -v1
	v_fmac_f32_e32 v1, 0x3377d1cf, v2
	v_fmac_f32_e32 v1, 0x3f317217, v2
	v_cmp_lt_f32_e64 s[54:55], |v2|, s95
	s_cmp_lt_u32 s70, 4
	v_add_u32_e32 v113, 0x200, v113
	v_cndmask_b32_e64 v1, v2, v1, s[54:55]
	v_cndmask_b32_e32 v2, 0, v240, vcc
	v_sub_f32_e32 v1, v1, v2
	v_add_f32_e32 v2, 1.0, v4
	v_cmp_gt_f32_e32 vcc, s76, v2
	v_sub_f32_e32 v0, v0, v1
	v_min_f32_e32 v1, 0, v3
	v_cndmask_b32_e64 v4, 0, 32, vcc
	v_ldexp_f32 v2, v2, v4
	v_log_f32_e32 v2, v2
	v_add_f32_e32 v4, v111, v6
	v_mul_f32_e64 v5, |v4|, s77
	v_exp_f32_e32 v5, v5
	v_mul_f32_e32 v3, 0x3f317217, v2
	v_fma_f32 v3, v2, s62, -v3
	v_fmac_f32_e32 v3, 0x3377d1cf, v2
	v_fmac_f32_e32 v3, 0x3f317217, v2
	v_cmp_lt_f32_e64 s[54:55], |v2|, s95
	v_mul_f32_e32 v0, 0x3d800000, v0
	s_nop 0
	v_cndmask_b32_e64 v2, v2, v3, s[54:55]
	v_cndmask_b32_e32 v3, 0, v240, vcc
	v_sub_f32_e32 v2, v2, v3
	v_sub_f32_e32 v1, v1, v2
	v_add_f32_e32 v2, 1.0, v5
	v_cmp_gt_f32_e32 vcc, s76, v2
	v_mul_f32_e32 v1, 0x3d800000, v1
	s_nop 0
	v_cndmask_b32_e64 v3, 0, 32, vcc
	v_ldexp_f32 v2, v2, v3
	v_log_f32_e32 v2, v2
	v_add_u32_e32 v3, 0x800, v99
	ds_write2_b32 v3, v0, v1 offset0:8 offset1:73
	v_min_f32_e32 v0, 0, v4
	v_add_f32_e32 v4, v111, v7
	v_mul_f32_e32 v1, 0x3f317217, v2
	v_mul_f32_e64 v5, |v4|, s77
	v_fma_f32 v1, v2, s62, -v1
	v_exp_f32_e32 v5, v5
	v_fmac_f32_e32 v1, 0x3377d1cf, v2
	v_fmac_f32_e32 v1, 0x3f317217, v2
	v_cmp_lt_f32_e64 s[54:55], |v2|, s95
	s_nop 1
	v_cndmask_b32_e64 v1, v2, v1, s[54:55]
	v_cndmask_b32_e32 v2, 0, v240, vcc
	v_sub_f32_e32 v1, v1, v2
	v_add_f32_e32 v2, 1.0, v5
	v_cmp_gt_f32_e32 vcc, s76, v2
	v_sub_f32_e32 v0, v0, v1
	v_min_f32_e32 v1, 0, v4
	v_cndmask_b32_e64 v5, 0, 32, vcc
	v_ldexp_f32 v2, v2, v5
	v_log_f32_e32 v2, v2
	v_cndmask_b32_e32 v6, 0, v240, vcc
	v_mul_f32_e32 v0, 0x3d800000, v0
	v_mul_f32_e32 v4, 0x3f317217, v2
	v_fma_f32 v4, v2, s62, -v4
	v_fmac_f32_e32 v4, 0x3377d1cf, v2
	v_fmac_f32_e32 v4, 0x3f317217, v2
	v_cmp_lt_f32_e64 s[54:55], |v2|, s95
	s_nop 1
	v_cndmask_b32_e64 v2, v2, v4, s[54:55]
	v_add_f32_e32 v4, v111, v8
	v_mul_f32_e64 v5, |v4|, s77
	v_exp_f32_e32 v5, v5
	v_sub_f32_e32 v2, v2, v6
	v_sub_f32_e32 v1, v1, v2
	v_mul_f32_e32 v1, 0x3d800000, v1
	v_add_f32_e32 v2, 1.0, v5
	v_cmp_gt_f32_e32 vcc, s76, v2
	ds_write2_b32 v3, v0, v1 offset0:138 offset1:203
	v_add_f32_e32 v3, v111, v9
; DI int crow(int r, int hi) { return (r & 3) + 8 * (r >> 2) + 4 * hi; }
; DI float logsig(float x) { return fminf(x, 0.f) - __logf(1.f + __expf(-fabsf(x))); }
; DI void phase_gla3(ArgsP a, int tb_, int l, bool with_ctx, char* shm, int vcu, int G) {
;     ...
;               acc = __builtin_amdgcn_mfma_f32_32x32x16_bf16(gfr, wfr, acc, 0, 0, 0);
; #pragma unroll
;               for (int r = 0; r < 16; ++r) LA[ldir * 4160 + (ljb * 32 + crow(r, hi)) * 65 + lkb * 32 + r32] = logsig(acc[r] + bias) * (1.f / 16.f); }
;             __syncthreads();
	v_cndmask_b32_e64 v5, 0, 32, vcc
	v_ldexp_f32 v2, v2, v5
	v_log_f32_e32 v2, v2
	v_min_f32_e32 v0, 0, v4
	v_mul_f32_e64 v4, |v3|, s77
	v_exp_f32_e32 v4, v4
	v_mul_f32_e32 v1, 0x3f317217, v2
	v_fma_f32 v1, v2, s62, -v1
	v_fmac_f32_e32 v1, 0x3377d1cf, v2
	v_fmac_f32_e32 v1, 0x3f317217, v2
	v_cmp_lt_f32_e64 s[54:55], |v2|, s95
	s_nop 1
	v_cndmask_b32_e64 v1, v2, v1, s[54:55]
	v_cndmask_b32_e32 v2, 0, v240, vcc
	v_sub_f32_e32 v1, v1, v2
	v_add_f32_e32 v2, 1.0, v4
	v_cmp_gt_f32_e32 vcc, s76, v2
	v_sub_f32_e32 v0, v0, v1
	v_min_f32_e32 v1, 0, v3
	v_cndmask_b32_e64 v4, 0, 32, vcc
	v_ldexp_f32 v2, v2, v4
	v_log_f32_e32 v2, v2
	v_add_f32_e32 v4, v111, v10
	v_mul_f32_e64 v5, |v4|, s77
	v_exp_f32_e32 v5, v5
	v_mul_f32_e32 v3, 0x3f317217, v2
	v_fma_f32 v3, v2, s62, -v3
	v_fmac_f32_e32 v3, 0x3377d1cf, v2
	v_fmac_f32_e32 v3, 0x3f317217, v2
	v_cmp_lt_f32_e64 s[54:55], |v2|, s95
	v_mul_f32_e32 v0, 0x3d800000, v0
	s_nop 0
	v_cndmask_b32_e64 v2, v2, v3, s[54:55]
	v_cndmask_b32_e32 v3, 0, v240, vcc
	v_sub_f32_e32 v2, v2, v3
	v_sub_f32_e32 v1, v1, v2
	v_add_f32_e32 v2, 1.0, v5
	v_cmp_gt_f32_e32 vcc, s76, v2
	v_mul_f32_e32 v1, 0x3d800000, v1
	s_nop 0
	v_cndmask_b32_e64 v3, 0, 32, vcc
	v_ldexp_f32 v2, v2, v3
	v_log_f32_e32 v2, v2
	v_add_u32_e32 v3, 0x1000, v99
	ds_write2_b32 v3, v0, v1 offset0:16 offset1:81
	v_min_f32_e32 v0, 0, v4
	v_add_f32_e32 v4, v111, v11
	v_mul_f32_e32 v1, 0x3f317217, v2
	v_mul_f32_e64 v5, |v4|, s77
	v_fma_f32 v1, v2, s62, -v1
	v_exp_f32_e32 v5, v5
	v_fmac_f32_e32 v1, 0x3377d1cf, v2
	v_fmac_f32_e32 v1, 0x3f317217, v2
	v_cmp_lt_f32_e64 s[54:55], |v2|, s95
	s_nop 1
	v_cndmask_b32_e64 v1, v2, v1, s[54:55]
	v_cndmask_b32_e32 v2, 0, v240, vcc
	v_sub_f32_e32 v1, v1, v2
	v_add_f32_e32 v2, 1.0, v5
	v_cmp_gt_f32_e32 vcc, s76, v2
	v_sub_f32_e32 v0, v0, v1
	v_min_f32_e32 v1, 0, v4
	v_cndmask_b32_e64 v5, 0, 32, vcc
	v_ldexp_f32 v2, v2, v5
	v_log_f32_e32 v2, v2
	v_cndmask_b32_e32 v6, 0, v240, vcc
	v_mul_f32_e32 v0, 0x3d800000, v0
	v_mul_f32_e32 v4, 0x3f317217, v2
	v_fma_f32 v4, v2, s62, -v4
	v_fmac_f32_e32 v4, 0x3377d1cf, v2
	v_fmac_f32_e32 v4, 0x3f317217, v2
	v_cmp_lt_f32_e64 s[54:55], |v2|, s95
	s_nop 1
	v_cndmask_b32_e64 v2, v2, v4, s[54:55]
	v_add_f32_e32 v4, v111, v12
	v_mul_f32_e64 v5, |v4|, s77
	v_exp_f32_e32 v5, v5
	v_sub_f32_e32 v2, v2, v6
	v_sub_f32_e32 v1, v1, v2
	v_mul_f32_e32 v1, 0x3d800000, v1
	v_add_f32_e32 v2, 1.0, v5
	v_cmp_gt_f32_e32 vcc, s76, v2
	ds_write2_b32 v3, v0, v1 offset0:146 offset1:211
	v_add_f32_e32 v3, v111, v13
	v_cndmask_b32_e64 v5, 0, 32, vcc
	v_ldexp_f32 v2, v2, v5
	v_log_f32_e32 v2, v2
	v_min_f32_e32 v0, 0, v4
	v_mul_f32_e64 v4, |v3|, s77
	v_exp_f32_e32 v4, v4
	v_mul_f32_e32 v1, 0x3f317217, v2
	v_fma_f32 v1, v2, s62, -v1
	v_fmac_f32_e32 v1, 0x3377d1cf, v2
	v_fmac_f32_e32 v1, 0x3f317217, v2
	v_cmp_lt_f32_e64 s[54:55], |v2|, s95
	s_nop 1
	v_cndmask_b32_e64 v1, v2, v1, s[54:55]
	v_cndmask_b32_e32 v2, 0, v240, vcc
	v_sub_f32_e32 v1, v1, v2
	v_add_f32_e32 v2, 1.0, v4
	v_cmp_gt_f32_e32 vcc, s76, v2
	v_sub_f32_e32 v0, v0, v1
	v_min_f32_e32 v1, 0, v3
	v_cndmask_b32_e64 v4, 0, 32, vcc
	v_ldexp_f32 v2, v2, v4
	v_log_f32_e32 v2, v2
	v_add_f32_e32 v4, v111, v14
	v_mul_f32_e64 v5, |v4|, s77
	v_exp_f32_e32 v5, v5
	v_mul_f32_e32 v3, 0x3f317217, v2
	v_fma_f32 v3, v2, s62, -v3
	v_fmac_f32_e32 v3, 0x3377d1cf, v2
	v_fmac_f32_e32 v3, 0x3f317217, v2
	v_cmp_lt_f32_e64 s[54:55], |v2|, s95
	v_mul_f32_e32 v0, 0x3d800000, v0
	s_nop 0
	v_cndmask_b32_e64 v2, v2, v3, s[54:55]
	v_cndmask_b32_e32 v3, 0, v240, vcc
	v_sub_f32_e32 v2, v2, v3
	v_sub_f32_e32 v1, v1, v2
	v_add_f32_e32 v2, 1.0, v5
	v_cmp_gt_f32_e32 vcc, s76, v2
	v_mul_f32_e32 v1, 0x3d800000, v1
	s_nop 0
	v_cndmask_b32_e64 v3, 0, 32, vcc
	v_ldexp_f32 v2, v2, v3
	v_log_f32_e32 v2, v2
	v_add_u32_e32 v3, 0x1800, v99
	ds_write2_b32 v3, v0, v1 offset0:24 offset1:89
	v_min_f32_e32 v0, 0, v4
	v_add_f32_e32 v4, v111, v15
	v_mul_f32_e32 v1, 0x3f317217, v2
	v_mul_f32_e64 v5, |v4|, s77
	v_fma_f32 v1, v2, s62, -v1
	v_exp_f32_e32 v5, v5
	v_fmac_f32_e32 v1, 0x3377d1cf, v2
	v_fmac_f32_e32 v1, 0x3f317217, v2
	v_cmp_lt_f32_e64 s[54:55], |v2|, s95
	s_nop 1
	v_cndmask_b32_e64 v1, v2, v1, s[54:55]
	v_cndmask_b32_e32 v2, 0, v240, vcc
	v_sub_f32_e32 v1, v1, v2
	v_add_f32_e32 v2, 1.0, v5
	v_cmp_gt_f32_e32 vcc, s76, v2
	v_sub_f32_e32 v0, v0, v1
	v_min_f32_e32 v1, 0, v4
	v_cndmask_b32_e64 v5, 0, 32, vcc
	v_ldexp_f32 v2, v2, v5
	v_log_f32_e32 v2, v2
	v_mul_f32_e32 v0, 0x3d800000, v0
	v_mul_f32_e32 v4, 0x3f317217, v2
	v_fma_f32 v4, v2, s62, -v4
	v_fmac_f32_e32 v4, 0x3377d1cf, v2
	v_fmac_f32_e32 v4, 0x3f317217, v2
	v_cmp_lt_f32_e64 s[54:55], |v2|, s95
	s_nop 1
	v_cndmask_b32_e64 v2, v2, v4, s[54:55]
	v_cndmask_b32_e32 v4, 0, v240, vcc
	v_sub_f32_e32 v2, v2, v4
	v_sub_f32_e32 v1, v1, v2
	v_mul_f32_e32 v1, 0x3d800000, v1
	ds_write2_b32 v3, v0, v1 offset0:154 offset1:219
	s_waitcnt lgkmcnt(0)
	s_barrier
; DI float scan64(float x, int lane) {
; #pragma unroll
;     for (int off = 1; off < 64; off <<= 1) { const float y = __int_as_float(__builtin_amdgcn_ds_bpermute((lane - off) << 2, __float_as_int(x))); if (lane >= off) x += y; }
;     return x;
; }
; DI void phase_gla3(ArgsP a, int tb_, int l, bool with_ctx, char* shm, int vcu, int G) {
;     ...
;             { const int dir = wid >> 2;
; #pragma unroll
;               for (int i = 0; i < 16; ++i) { const int kd = (wid & 3) * 16 + i, jj = dir ? 63 - lane : lane; const float x = scan64(LA[dir * 4160 + jj * 65 + kd], lane); LA[dir * 4160 + jj * 65 + kd] = x; } }
	s_cselect_b32 s54, 3, 0x47
	s_cselect_b32 s55, s74, s94
	s_add_i32 s70, s70, 8
	ds_read2_b32 v[0:1], v67 offset1:1
	ds_read2_b32 v[2:3], v67 offset0:2 offset1:3
	ds_read2_b32 v[4:5], v67 offset0:4 offset1:5
	ds_read2_b32 v[6:7], v67 offset0:6 offset1:7
	ds_read2_b32 v[8:9], v67 offset0:8 offset1:9
	ds_read2_b32 v[10:11], v67 offset0:10 offset1:11
	ds_read2_b32 v[14:15], v67 offset0:12 offset1:13
	ds_read2_b32 v[114:115], v67 offset0:14 offset1:15
	s_waitcnt lgkmcnt(0)
	v_add_f32_dpp v0, v0, v0 row_shr:1 row_mask:0xf bank_mask:0xf bound_ctrl:1
	v_add_f32_dpp v1, v1, v1 row_shr:1 row_mask:0xf bank_mask:0xf bound_ctrl:1
	v_add_f32_dpp v2, v2, v2 row_shr:1 row_mask:0xf bank_mask:0xf bound_ctrl:1
	v_add_f32_dpp v3, v3, v3 row_shr:1 row_mask:0xf bank_mask:0xf bound_ctrl:1
	v_add_f32_dpp v4, v4, v4 row_shr:1 row_mask:0xf bank_mask:0xf bound_ctrl:1
	v_add_f32_dpp v5, v5, v5 row_shr:1 row_mask:0xf bank_mask:0xf bound_ctrl:1
	v_add_f32_dpp v6, v6, v6 row_shr:1 row_mask:0xf bank_mask:0xf bound_ctrl:1
	v_add_f32_dpp v7, v7, v7 row_shr:1 row_mask:0xf bank_mask:0xf bound_ctrl:1
	v_add_f32_dpp v8, v8, v8 row_shr:1 row_mask:0xf bank_mask:0xf bound_ctrl:1
	v_add_f32_dpp v9, v9, v9 row_shr:1 row_mask:0xf bank_mask:0xf bound_ctrl:1
	v_add_f32_dpp v10, v10, v10 row_shr:1 row_mask:0xf bank_mask:0xf bound_ctrl:1
	v_add_f32_dpp v11, v11, v11 row_shr:1 row_mask:0xf bank_mask:0xf bound_ctrl:1
	v_add_f32_dpp v14, v14, v14 row_shr:1 row_mask:0xf bank_mask:0xf bound_ctrl:1
	v_add_f32_dpp v15, v15, v15 row_shr:1 row_mask:0xf bank_mask:0xf bound_ctrl:1
	v_add_f32_dpp v114, v114, v114 row_shr:1 row_mask:0xf bank_mask:0xf bound_ctrl:1
	v_add_f32_dpp v115, v115, v115 row_shr:1 row_mask:0xf bank_mask:0xf bound_ctrl:1
	v_add_f32_dpp v0, v0, v0 row_shr:2 row_mask:0xf bank_mask:0xf bound_ctrl:1
	v_add_f32_dpp v1, v1, v1 row_shr:2 row_mask:0xf bank_mask:0xf bound_ctrl:1
	v_add_f32_dpp v2, v2, v2 row_shr:2 row_mask:0xf bank_mask:0xf bound_ctrl:1
	v_add_f32_dpp v3, v3, v3 row_shr:2 row_mask:0xf bank_mask:0xf bound_ctrl:1
	v_add_f32_dpp v4, v4, v4 row_shr:2 row_mask:0xf bank_mask:0xf bound_ctrl:1
	v_add_f32_dpp v5, v5, v5 row_shr:2 row_mask:0xf bank_mask:0xf bound_ctrl:1
	v_add_f32_dpp v6, v6, v6 row_shr:2 row_mask:0xf bank_mask:0xf bound_ctrl:1
	v_add_f32_dpp v7, v7, v7 row_shr:2 row_mask:0xf bank_mask:0xf bound_ctrl:1
	v_add_f32_dpp v8, v8, v8 row_shr:2 row_mask:0xf bank_mask:0xf bound_ctrl:1
	v_add_f32_dpp v9, v9, v9 row_shr:2 row_mask:0xf bank_mask:0xf bound_ctrl:1
	v_add_f32_dpp v10, v10, v10 row_shr:2 row_mask:0xf bank_mask:0xf bound_ctrl:1
	v_add_f32_dpp v11, v11, v11 row_shr:2 row_mask:0xf bank_mask:0xf bound_ctrl:1
	v_add_f32_dpp v14, v14, v14 row_shr:2 row_mask:0xf bank_mask:0xf bound_ctrl:1
	v_add_f32_dpp v15, v15, v15 row_shr:2 row_mask:0xf bank_mask:0xf bound_ctrl:1
	v_add_f32_dpp v114, v114, v114 row_shr:2 row_mask:0xf bank_mask:0xf bound_ctrl:1
	v_add_f32_dpp v115, v115, v115 row_shr:2 row_mask:0xf bank_mask:0xf bound_ctrl:1
	v_add_f32_dpp v0, v0, v0 row_shr:4 row_mask:0xf bank_mask:0xf bound_ctrl:1
	v_add_f32_dpp v1, v1, v1 row_shr:4 row_mask:0xf bank_mask:0xf bound_ctrl:1
	v_add_f32_dpp v2, v2, v2 row_shr:4 row_mask:0xf bank_mask:0xf bound_ctrl:1
	v_add_f32_dpp v3, v3, v3 row_shr:4 row_mask:0xf bank_mask:0xf bound_ctrl:1
	v_add_f32_dpp v4, v4, v4 row_shr:4 row_mask:0xf bank_mask:0xf bound_ctrl:1
	v_add_f32_dpp v5, v5, v5 row_shr:4 row_mask:0xf bank_mask:0xf bound_ctrl:1
	v_add_f32_dpp v6, v6, v6 row_shr:4 row_mask:0xf bank_mask:0xf bound_ctrl:1
	v_add_f32_dpp v7, v7, v7 row_shr:4 row_mask:0xf bank_mask:0xf bound_ctrl:1
	v_add_f32_dpp v8, v8, v8 row_shr:4 row_mask:0xf bank_mask:0xf bound_ctrl:1
	v_add_f32_dpp v9, v9, v9 row_shr:4 row_mask:0xf bank_mask:0xf bound_ctrl:1
	v_add_f32_dpp v10, v10, v10 row_shr:4 row_mask:0xf bank_mask:0xf bound_ctrl:1
	v_add_f32_dpp v11, v11, v11 row_shr:4 row_mask:0xf bank_mask:0xf bound_ctrl:1
	v_add_f32_dpp v14, v14, v14 row_shr:4 row_mask:0xf bank_mask:0xf bound_ctrl:1
	v_add_f32_dpp v15, v15, v15 row_shr:4 row_mask:0xf bank_mask:0xf bound_ctrl:1
	v_add_f32_dpp v114, v114, v114 row_shr:4 row_mask:0xf bank_mask:0xf bound_ctrl:1
	v_add_f32_dpp v115, v115, v115 row_shr:4 row_mask:0xf bank_mask:0xf bound_ctrl:1
	v_add_f32_dpp v0, v0, v0 row_shr:8 row_mask:0xf bank_mask:0xf bound_ctrl:1
	v_add_f32_dpp v1, v1, v1 row_shr:8 row_mask:0xf bank_mask:0xf bound_ctrl:1
	v_add_f32_dpp v2, v2, v2 row_shr:8 row_mask:0xf bank_mask:0xf bound_ctrl:1
	v_add_f32_dpp v3, v3, v3 row_shr:8 row_mask:0xf bank_mask:0xf bound_ctrl:1
	v_add_f32_dpp v4, v4, v4 row_shr:8 row_mask:0xf bank_mask:0xf bound_ctrl:1
	v_add_f32_dpp v5, v5, v5 row_shr:8 row_mask:0xf bank_mask:0xf bound_ctrl:1
	v_add_f32_dpp v6, v6, v6 row_shr:8 row_mask:0xf bank_mask:0xf bound_ctrl:1
	v_add_f32_dpp v7, v7, v7 row_shr:8 row_mask:0xf bank_mask:0xf bound_ctrl:1
	v_add_f32_dpp v8, v8, v8 row_shr:8 row_mask:0xf bank_mask:0xf bound_ctrl:1
	v_add_f32_dpp v9, v9, v9 row_shr:8 row_mask:0xf bank_mask:0xf bound_ctrl:1
	v_add_f32_dpp v10, v10, v10 row_shr:8 row_mask:0xf bank_mask:0xf bound_ctrl:1
	v_add_f32_dpp v11, v11, v11 row_shr:8 row_mask:0xf bank_mask:0xf bound_ctrl:1
	v_add_f32_dpp v14, v14, v14 row_shr:8 row_mask:0xf bank_mask:0xf bound_ctrl:1
	v_add_f32_dpp v15, v15, v15 row_shr:8 row_mask:0xf bank_mask:0xf bound_ctrl:1
	v_add_f32_dpp v114, v114, v114 row_shr:8 row_mask:0xf bank_mask:0xf bound_ctrl:1
	v_add_f32_dpp v115, v115, v115 row_shr:8 row_mask:0xf bank_mask:0xf bound_ctrl:1
	v_add_f32_dpp v0, v0, v0 row_bcast:15 row_mask:0xa bank_mask:0xf
	v_add_f32_dpp v1, v1, v1 row_bcast:15 row_mask:0xa bank_mask:0xf
	v_add_f32_dpp v2, v2, v2 row_bcast:15 row_mask:0xa bank_mask:0xf
; DI unsigned cvtpk(float lo, float hi) { f32x2_t v = {lo, hi}; bf16x2_t b = __builtin_convertvector(v, bf16x2_t); return __builtin_bit_cast(unsigned, b); }
; DI float bflo(unsigned u) { return __uint_as_float(u << 16); }
; DI float bfhi(unsigned u) { return __uint_as_float(u & 0xffff0000u); }
; DI void phase_gla3(ArgsP a, int tb_, int l, bool with_ctx, char* shm, int vcu, int G) {
;     ...
;               for (int i = 0; i < 16; ++i) { const int kd = (wid & 3) * 16 + i, jj = dir ? 63 - lane : lane; const float x = scan64(LA[dir * 4160 + jj * 65 + kd], lane); LA[dir * 4160 + jj * 65 + kd] = x; } }
;             __syncthreads();
;             { const float qv[8] = {bflo(qw.x), bfhi(qw.x), bflo(qw.y), bfhi(qw.y), bflo(qw.z), bfhi(qw.z), bflo(qw.w), bfhi(qw.w)};
;               const float kv[8] = {bflo(kw.x), bfhi(kw.x), bflo(kw.y), bfhi(kw.y), bflo(kw.z), bfhi(kw.z), bflo(kw.w), bfhi(kw.w)};
; #pragma unroll
;               for (int dir = 0; dir < 2; ++dir) { float qt[8], kt[8];
; #pragma unroll
;                   for (int kk = 0; kk < 8; ++kk) { const float e = LA[dir * 4160 + j * 65 + kg * 8 + kk]; qt[kk] = qv[kk] * 0.125f * __expf(e); kt[kk] = kv[kk] * __expf(-e); }
;                   u32x4 w; w.x = cvtpk(qt[0], qt[1]); w.y = cvtpk(qt[2], qt[3]); w.z = cvtpk(qt[4], qt[5]); w.w = cvtpk(qt[6], qt[7]); *(u32x4*)(QT + dir * 9216 + j * 144 + kg * 16) = w;
;                   u32x4 w2; w2.x = cvtpk(kt[0], kt[1]); w2.y = cvtpk(kt[2], kt[3]); w2.z = cvtpk(kt[4], kt[5]); w2.w = cvtpk(kt[6], kt[7]); *(u32x4*)(KTt + dir * 9216 + j * 144 + kg * 16) = w2; }
	v_add_f32_dpp v3, v3, v3 row_bcast:15 row_mask:0xa bank_mask:0xf
	v_add_f32_dpp v4, v4, v4 row_bcast:15 row_mask:0xa bank_mask:0xf
	v_add_f32_dpp v5, v5, v5 row_bcast:15 row_mask:0xa bank_mask:0xf
	v_add_f32_dpp v6, v6, v6 row_bcast:15 row_mask:0xa bank_mask:0xf
	v_add_f32_dpp v7, v7, v7 row_bcast:15 row_mask:0xa bank_mask:0xf
	v_add_f32_dpp v8, v8, v8 row_bcast:15 row_mask:0xa bank_mask:0xf
	v_add_f32_dpp v9, v9, v9 row_bcast:15 row_mask:0xa bank_mask:0xf
	v_add_f32_dpp v10, v10, v10 row_bcast:15 row_mask:0xa bank_mask:0xf
	v_add_f32_dpp v11, v11, v11 row_bcast:15 row_mask:0xa bank_mask:0xf
	v_add_f32_dpp v14, v14, v14 row_bcast:15 row_mask:0xa bank_mask:0xf
	v_add_f32_dpp v15, v15, v15 row_bcast:15 row_mask:0xa bank_mask:0xf
	v_add_f32_dpp v114, v114, v114 row_bcast:15 row_mask:0xa bank_mask:0xf
	v_add_f32_dpp v115, v115, v115 row_bcast:15 row_mask:0xa bank_mask:0xf
	v_add_f32_dpp v0, v0, v0 row_bcast:31 row_mask:0xc bank_mask:0xf
	v_add_f32_dpp v1, v1, v1 row_bcast:31 row_mask:0xc bank_mask:0xf
	v_add_f32_dpp v2, v2, v2 row_bcast:31 row_mask:0xc bank_mask:0xf
	v_add_f32_dpp v3, v3, v3 row_bcast:31 row_mask:0xc bank_mask:0xf
	v_add_f32_dpp v4, v4, v4 row_bcast:31 row_mask:0xc bank_mask:0xf
	v_add_f32_dpp v5, v5, v5 row_bcast:31 row_mask:0xc bank_mask:0xf
	v_add_f32_dpp v6, v6, v6 row_bcast:31 row_mask:0xc bank_mask:0xf
	v_add_f32_dpp v7, v7, v7 row_bcast:31 row_mask:0xc bank_mask:0xf
	v_add_f32_dpp v8, v8, v8 row_bcast:31 row_mask:0xc bank_mask:0xf
	v_add_f32_dpp v9, v9, v9 row_bcast:31 row_mask:0xc bank_mask:0xf
	v_add_f32_dpp v10, v10, v10 row_bcast:31 row_mask:0xc bank_mask:0xf
	v_add_f32_dpp v11, v11, v11 row_bcast:31 row_mask:0xc bank_mask:0xf
	v_add_f32_dpp v14, v14, v14 row_bcast:31 row_mask:0xc bank_mask:0xf
	v_add_f32_dpp v15, v15, v15 row_bcast:31 row_mask:0xc bank_mask:0xf
	v_add_f32_dpp v114, v114, v114 row_bcast:31 row_mask:0xc bank_mask:0xf
	v_add_f32_dpp v115, v115, v115 row_bcast:31 row_mask:0xc bank_mask:0xf
	ds_write2_b32 v67, v0, v1 offset1:1
	ds_write2_b32 v67, v2, v3 offset0:2 offset1:3
	ds_write2_b32 v67, v4, v5 offset0:4 offset1:5
	ds_write2_b32 v67, v6, v7 offset0:6 offset1:7
	ds_write2_b32 v67, v8, v9 offset0:8 offset1:9
	ds_write2_b32 v67, v10, v11 offset0:10 offset1:11
	ds_write2_b32 v67, v14, v15 offset0:12 offset1:13
	ds_write2_b32 v67, v114, v115 offset0:14 offset1:15
	v_lshlrev_b32_e32 v12, 16, v48
	s_waitcnt lgkmcnt(0)
	s_barrier
	ds_read2_b32 v[0:1], v100 offset1:1
	ds_read2_b32 v[2:3], v100 offset0:2 offset1:3
	ds_read2_b32 v[4:5], v100 offset0:4 offset1:5
	ds_read2_b32 v[6:7], v100 offset0:6 offset1:7
	v_and_b32_e32 v13, 0xffff0000, v48
	v_lshlrev_b32_e32 v10, 16, v52
	v_and_b32_e32 v11, 0xffff0000, v52
	s_waitcnt lgkmcnt(3)
	v_mul_f32_e32 v8, 0x3fb8aa3b, v0
	v_mul_f32_e32 v0, 0xbfb8aa3b, v0
	v_mul_f32_e32 v9, 0x3fb8aa3b, v1
	v_mul_f32_e32 v1, 0xbfb8aa3b, v1
	v_exp_f32_e32 v0, v0
	v_exp_f32_e32 v1, v1
	v_lshlrev_b32_e32 v52, 16, v53
	v_and_b32_e32 v53, 0xffff0000, v53
	v_pk_mul_f32 v[52:53], v[52:53], s[90:91] op_sel_hi:[1,0]
	v_pk_mul_f32 v[14:15], v[0:1], v[12:13]
	s_waitcnt lgkmcnt(2)
	v_mul_f32_e32 v1, 0xbfb8aa3b, v2
	v_mul_f32_e32 v0, 0x3fb8aa3b, v2
	v_exp_f32_e32 v2, v1
	v_mul_f32_e32 v1, 0x3fb8aa3b, v3
	v_exp_f32_e32 v0, v0
	v_exp_f32_e32 v1, v1
	v_mul_f32_e32 v3, 0xbfb8aa3b, v3
	v_exp_f32_e32 v3, v3
	v_lshlrev_b32_e32 v48, 16, v49
	v_pk_mul_f32 v[114:115], v[52:53], v[0:1]
	v_and_b32_e32 v49, 0xffff0000, v49
	s_waitcnt lgkmcnt(1)
	v_mul_f32_e32 v1, 0xbfb8aa3b, v4
	v_pk_mul_f32 v[116:117], v[2:3], v[48:49]
	v_mul_f32_e32 v0, 0x3fb8aa3b, v4
	v_exp_f32_e32 v2, v1
	v_mul_f32_e32 v1, 0x3fb8aa3b, v5
	v_exp_f32_e32 v0, v0
	v_exp_f32_e32 v1, v1
	v_mul_f32_e32 v3, 0xbfb8aa3b, v5
	v_exp_f32_e32 v3, v3
	v_exp_f32_e32 v8, v8
	v_pk_mul_f32 v[4:5], v[118:119], v[0:1]
	s_waitcnt lgkmcnt(0)
	v_mul_f32_e32 v1, 0xbfb8aa3b, v6
	v_pk_mul_f32 v[122:123], v[2:3], v[120:121]
	v_mul_f32_e32 v0, 0x3fb8aa3b, v6
	v_exp_f32_e32 v2, v1
	v_mul_f32_e32 v1, 0x3fb8aa3b, v7
	v_exp_f32_e32 v9, v9
	v_exp_f32_e32 v0, v0
	v_exp_f32_e32 v1, v1
	v_mul_f32_e32 v3, 0xbfb8aa3b, v7
	v_exp_f32_e32 v3, v3
	v_pk_mul_f32 v[10:11], v[10:11], s[90:91] op_sel_hi:[1,0]
	v_pk_mul_f32 v[6:7], v[54:55], v[0:1]
	v_pk_mul_f32 v[8:9], v[10:11], v[8:9]
	v_pk_mul_f32 v[124:125], v[2:3], v[50:51]
	v_cvt_pk_bf16_f32 v0, v8, v9
	v_cvt_pk_bf16_f32 v1, v114, v115
	v_cvt_pk_bf16_f32 v2, v4, v5
	v_cvt_pk_bf16_f32 v3, v6, v7
	ds_write_b128 v101, v[0:3] offset:33792
	v_cvt_pk_bf16_f32 v0, v14, v15
	v_cvt_pk_bf16_f32 v1, v116, v117
	v_cvt_pk_bf16_f32 v2, v122, v123
	v_cvt_pk_bf16_f32 v3, v124, v125
	ds_write_b128 v101, v[0:3] offset:52224
	v_add_u32_e32 v0, 0x4100, v100
	ds_read2_b32 v[0:1], v0 offset1:1
	v_add_u32_e32 v2, 0x4108, v100
	v_add_u32_e32 v4, 0x4110, v100
	v_add_u32_e32 v6, 0x4118, v100
	ds_read2_b32 v[2:3], v2 offset1:1
	ds_read2_b32 v[4:5], v4 offset1:1
	ds_read2_b32 v[6:7], v6 offset1:1
	s_waitcnt lgkmcnt(3)
	v_mul_f32_e32 v8, 0x3fb8aa3b, v0
	v_mul_f32_e32 v0, 0xbfb8aa3b, v0
	v_mul_f32_e32 v9, 0x3fb8aa3b, v1
	v_mul_f32_e32 v1, 0xbfb8aa3b, v1
	v_exp_f32_e32 v8, v8
	v_exp_f32_e32 v0, v0
	v_exp_f32_e32 v9, v9
	v_exp_f32_e32 v1, v1
	s_waitcnt lgkmcnt(2)
	v_mul_f32_e32 v14, 0x3fb8aa3b, v2
	v_mul_f32_e32 v2, 0xbfb8aa3b, v2
	v_mul_f32_e32 v15, 0x3fb8aa3b, v3
	v_mul_f32_e32 v3, 0xbfb8aa3b, v3
	v_exp_f32_e32 v14, v14
	v_exp_f32_e32 v2, v2
	v_exp_f32_e32 v15, v15
	v_exp_f32_e32 v3, v3
	v_pk_mul_f32 v[8:9], v[10:11], v[8:9]
	v_pk_mul_f32 v[10:11], v[0:1], v[12:13]
	s_waitcnt lgkmcnt(1)
	v_mul_f32_e32 v1, 0xbfb8aa3b, v4
	v_pk_mul_f32 v[12:13], v[52:53], v[14:15]
	v_pk_mul_f32 v[14:15], v[2:3], v[48:49]
	v_exp_f32_e32 v2, v1
	v_mul_f32_e32 v1, 0x3fb8aa3b, v5
	v_mul_f32_e32 v3, 0xbfb8aa3b, v5
	s_waitcnt lgkmcnt(0)
; DI unsigned cvtpk(float lo, float hi) { f32x2_t v = {lo, hi}; bf16x2_t b = __builtin_convertvector(v, bf16x2_t); return __builtin_bit_cast(unsigned, b); }
; DI bf16_t f2bf(float f) { return (bf16_t)(cvtpk(f, f) & 0xffffu); }
; DI int crow(int r, int hi) { return (r & 3) + 8 * (r >> 2) + 4 * hi; }
; DI void phase_gla3(ArgsP a, int tb_, int l, bool with_ctx, char* shm, int vcu, int G) {
;     ...
;                   u32x4 w2; w2.x = cvtpk(kt[0], kt[1]); w2.y = cvtpk(kt[2], kt[3]); w2.z = cvtpk(kt[4], kt[5]); w2.w = cvtpk(kt[6], kt[7]); *(u32x4*)(KTt + dir * 9216 + j * 144 + kg * 16) = w2; }
;               const unsigned vv[8] = {v0.x, v0.y, v0.z, v0.w, v1.x, v1.y, v1.z, v1.w};
; #pragma unroll
;               for (int q = 0; q < 8; ++q) { *(bf16_t*)(VT + (kg * 16 + 2 * q) * 144 + j * 2) = (bf16_t)(vv[q] & 0xffffu); *(bf16_t*)(VT + (kg * 16 + 2 * q + 1) * 144 + j * 2) = (bf16_t)(vv[q] >> 16); } }
;             const u32x4* rp = (const u32x4*)(zr + (size_t)(m0 + j) * ZR + 1536 + h * 128 + kg * 16); const u32x4 r0 = rp[0], r1 = rp[1];
;             const int oib = wid >> 2, ovb = wid & 3;
;             bf16x8 sfr[2][4];
; #pragma unroll
;             for (int dir = 0; dir < 2; ++dir) { const bf16_t* sp = ST + ((size_t)((b * 4 + h) * 2 + dir) * NSLOT + (dir ? slot_b : slot_f)) * 8192 + (size_t)(ovb * 32 + r32) * 64 + 8 * hi;
; #pragma unroll
;                 for (int s4 = 0; s4 < 4; ++s4) sfr[dir][s4] = *(const bf16x8*)(sp + 16 * s4); }
;             __syncthreads();
;             { const int dir = wid >> 2, ib = (wid >> 1) & 1, jb = wid & 1; f32x16 acc;
; #pragma unroll
;               for (int r = 0; r < 16; ++r) acc[r] = 0.f;
; #pragma unroll
;               for (int s4 = 0; s4 < 4; ++s4) { const bf16x8 af = *(const bf16x8*)(QT + dir * 9216 + (ib * 32 + r32) * 144 + (16 * s4 + 8 * hi) * 2); const bf16x8 bfr = *(const bf16x8*)(KTt + dir * 9216 + (jb * 32 + r32) * 144 + (16 * s4 + 8 * hi) * 2);
;                   acc = __builtin_amdgcn_mfma_f32_32x32x16_bf16(af, bfr, acc, 0, 0, 0); }
;               const int jc = jb * 32 + r32;
; #pragma unroll
;               for (int r = 0; r < 16; ++r) { const int ir = ib * 32 + crow(r, hi); const bool keep = dir ? (jc >= ir) : (jc <= ir); *(bf16_t*)(AM + dir * 9216 + ir * 144 + jc * 2) = f2bf(keep ? acc[r] : 0.f); } }
;             __syncthreads();
	v_mul_f32_e32 v5, 0xbfb8aa3b, v6
	v_mul_f32_e32 v0, 0x3fb8aa3b, v4
	v_mul_f32_e32 v4, 0x3fb8aa3b, v6
	v_exp_f32_e32 v6, v5
	v_mul_f32_e32 v5, 0x3fb8aa3b, v7
	v_exp_f32_e32 v0, v0
	v_exp_f32_e32 v1, v1
	v_exp_f32_e32 v4, v4
	v_exp_f32_e32 v5, v5
	v_mul_f32_e32 v7, 0xbfb8aa3b, v7
	v_exp_f32_e32 v3, v3
	v_exp_f32_e32 v7, v7
	v_pk_mul_f32 v[48:49], v[118:119], v[0:1]
	v_pk_mul_f32 v[4:5], v[54:55], v[4:5]
	v_pk_mul_f32 v[52:53], v[2:3], v[120:121]
	v_pk_mul_f32 v[6:7], v[6:7], v[50:51]
	v_cvt_pk_bf16_f32 v0, v8, v9
	v_cvt_pk_bf16_f32 v1, v12, v13
	v_cvt_pk_bf16_f32 v2, v48, v49
	v_cvt_pk_bf16_f32 v3, v4, v5
	s_add_u32 s54, s33, s54
	ds_write_b128 v101, v[0:3] offset:43008
	v_cvt_pk_bf16_f32 v0, v10, v11
	v_cvt_pk_bf16_f32 v1, v14, v15
	v_cvt_pk_bf16_f32 v2, v52, v53
	v_cvt_pk_bf16_f32 v3, v6, v7
	v_add_u32_e32 v48, s55, v112
	s_addc_u32 s55, s2, 0
	ds_write_b128 v101, v[0:3] offset:61440
	v_mov_b32_dpp v212, v44 row_ror:8 row_mask:0xf bank_mask:0xf
	v_perm_b32 v213, v212, v44, v210
	ds_write_b32 v209, v213
	v_mov_b32_dpp v214, v45 row_ror:8 row_mask:0xf bank_mask:0xf
	v_perm_b32 v215, v214, v45, v210
	ds_write_b32 v209, v215 offset:288
	v_mov_b32_dpp v212, v46 row_ror:8 row_mask:0xf bank_mask:0xf
	v_perm_b32 v213, v212, v46, v210
	ds_write_b32 v209, v213 offset:576
	v_mov_b32_dpp v214, v47 row_ror:8 row_mask:0xf bank_mask:0xf
	v_perm_b32 v215, v214, v47, v210
	ds_write_b32 v209, v215 offset:864
	v_mov_b32_dpp v212, v40 row_ror:8 row_mask:0xf bank_mask:0xf
	v_perm_b32 v213, v212, v40, v210
	ds_write_b32 v209, v213 offset:1152
	v_mov_b32_dpp v214, v41 row_ror:8 row_mask:0xf bank_mask:0xf
	v_perm_b32 v215, v214, v41, v210
	ds_write_b32 v209, v215 offset:1440
	v_mov_b32_dpp v212, v42 row_ror:8 row_mask:0xf bank_mask:0xf
	v_perm_b32 v213, v212, v42, v210
	ds_write_b32 v209, v213 offset:1728
	v_mov_b32_dpp v214, v43 row_ror:8 row_mask:0xf bank_mask:0xf
	v_perm_b32 v215, v214, v43, v210
	ds_write_b32 v209, v215 offset:2016
	v_mad_i64_i32 v[0:1], vcc, v48, s67, v[86:87]
	s_lshl_b64 s[54:55], s[54:55], 14
	global_load_dwordx4 v[40:43], v[0:1], off offset:3088
	global_load_dwordx4 v[44:47], v[0:1], off offset:3072
	global_load_dwordx4 v[50:53], v[82:83], off offset:-64
	global_load_dwordx4 v[114:117], v[82:83], off offset:-32
	global_load_dwordx4 v[118:121], v[82:83], off
	global_load_dwordx4 v[122:125], v[82:83], off offset:32
	v_lshl_add_u64 v[0:1], v[70:71], 0, s[54:55]
	global_load_dwordx4 v[126:129], v[0:1], off
	global_load_dwordx4 v[130:133], v[0:1], off offset:32
	global_load_dwordx4 v[134:137], v[0:1], off offset:64
	global_load_dwordx4 v[138:141], v[0:1], off offset:96
	s_waitcnt lgkmcnt(0)
	s_barrier
	ds_read_b128 v[0:3], v103 offset:33792
	ds_read_b128 v[4:7], v104 offset:52224
	s_waitcnt lgkmcnt(0)
	v_mfma_f32_32x32x16_bf16 v[0:15], v[0:3], v[4:7], 0
	ds_read_b128 v[142:145], v103 offset:33824
	ds_read_b128 v[146:149], v104 offset:52256
	s_add_u32 s33, s33, -8
	v_lshl_add_u64 v[82:83], v[82:83], 0, s[88:89]
	v_add_u32_e32 v112, 0x200, v112
	s_addc_u32 s2, s2, -1
	s_waitcnt lgkmcnt(0)
	v_mfma_f32_32x32x16_bf16 v[0:15], v[142:145], v[146:149], v[0:15]
	ds_read_b128 v[142:145], v103 offset:33856
	ds_read_b128 v[146:149], v104 offset:52288
	s_waitcnt lgkmcnt(0)
	v_mfma_f32_32x32x16_bf16 v[0:15], v[142:145], v[146:149], v[0:15]
	ds_read_b128 v[142:145], v103 offset:33888
	ds_read_b128 v[146:149], v104 offset:52320
	s_waitcnt lgkmcnt(0)
	v_mfma_f32_32x32x16_bf16 v[0:15], v[142:145], v[146:149], v[0:15]
	s_nop 11
	v_cvt_pk_bf16_f32 v0, v0, s0
	v_cndmask_b32_e64 v0, 0, v0, s[18:19]
	ds_write_b16 v105, v0
	v_cvt_pk_bf16_f32 v0, v1, s0
	v_cndmask_b32_e64 v0, 0, v0, s[20:21]
	ds_write_b16 v105, v0 offset:144
	v_cvt_pk_bf16_f32 v0, v2, s0
	v_cndmask_b32_e64 v0, 0, v0, s[22:23]
	ds_write_b16 v105, v0 offset:288
	v_cvt_pk_bf16_f32 v0, v3, s0
	v_cndmask_b32_e64 v0, 0, v0, s[24:25]
	ds_write_b16 v105, v0 offset:432
	v_cvt_pk_bf16_f32 v0, v4, s0
	v_cndmask_b32_e64 v0, 0, v0, s[26:27]
	ds_write_b16 v105, v0 offset:1152
	v_cvt_pk_bf16_f32 v0, v5, s0
	v_cndmask_b32_e64 v0, 0, v0, s[28:29]
	ds_write_b16 v105, v0 offset:1296
	v_cvt_pk_bf16_f32 v0, v6, s0
	v_cndmask_b32_e64 v0, 0, v0, s[30:31]
	ds_write_b16 v105, v0 offset:1440
	v_cvt_pk_bf16_f32 v0, v7, s0
	v_cndmask_b32_e64 v0, 0, v0, s[34:35]
	ds_write_b16 v105, v0 offset:1584
	v_cvt_pk_bf16_f32 v0, v8, s0
	v_cndmask_b32_e64 v0, 0, v0, s[36:37]
	ds_write_b16 v105, v0 offset:2304
	v_cvt_pk_bf16_f32 v0, v9, s0
	v_cndmask_b32_e64 v0, 0, v0, s[38:39]
	ds_write_b16 v105, v0 offset:2448
	v_cvt_pk_bf16_f32 v0, v10, s0
	v_cndmask_b32_e64 v0, 0, v0, s[40:41]
	ds_write_b16 v105, v0 offset:2592
	v_cvt_pk_bf16_f32 v0, v11, s0
	v_cndmask_b32_e64 v0, 0, v0, s[42:43]
	ds_write_b16 v105, v0 offset:2736
	v_cvt_pk_bf16_f32 v0, v12, s0
	v_cndmask_b32_e64 v0, 0, v0, s[44:45]
	ds_write_b16 v105, v0 offset:3456
	v_cvt_pk_bf16_f32 v0, v13, s0
	v_cndmask_b32_e64 v0, 0, v0, s[46:47]
	ds_write_b16 v105, v0 offset:3600
	v_cvt_pk_bf16_f32 v0, v14, s0
	v_cndmask_b32_e64 v0, 0, v0, s[48:49]
	ds_write_b16 v105, v0 offset:3744
	v_cvt_pk_bf16_f32 v0, v15, s0
	v_cndmask_b32_e64 v0, 0, v0, s[50:51]
	ds_write_b16 v105, v0 offset:3888
	s_waitcnt lgkmcnt(0)
	s_barrier
; DI int crow(int r, int hi) { return (r & 3) + 8 * (r >> 2) + 4 * hi; }
; DI void phase_gla3(ArgsP a, int tb_, int l, bool with_ctx, char* shm, int vcu, int G) {
;     ...
;             { f32x16 acc;
; #pragma unroll
;               for (int r = 0; r < 16; ++r) acc[r] = 0.f;
; #pragma unroll
;               for (int dir = 0; dir < 2; ++dir) {
; #pragma unroll
;                   for (int s4 = 0; s4 < 4; ++s4) { const bf16x8 af = *(const bf16x8*)(AM + dir * 9216 + (oib * 32 + r32) * 144 + (16 * s4 + 8 * hi) * 2); const bf16x8 bfr = *(const bf16x8*)(VT + (ovb * 32 + r32) * 144 + (16 * s4 + 8 * hi) * 2);
;                       acc = __builtin_amdgcn_mfma_f32_32x32x16_bf16(af, bfr, acc, 0, 0, 0); }
; #pragma unroll
;                   for (int s4 = 0; s4 < 4; ++s4) { const bf16x8 af = *(const bf16x8*)(QT + dir * 9216 + (oib * 32 + r32) * 144 + (16 * s4 + 8 * hi) * 2);
;                       acc = __builtin_amdgcn_mfma_f32_32x32x16_bf16(af, sfr[dir][s4], acc, 0, 0, 0); } }
; #pragma unroll
;               for (int r = 0; r < 16; ++r) OS[(oib * 32 + crow(r, hi)) * 132 + ovb * 32 + r32] = acc[r]; }
;             __syncthreads();
	ds_read_b128 v[0:3], v106
	ds_read_b128 v[142:145], v107
	s_waitcnt lgkmcnt(0)
	v_mfma_f32_32x32x16_bf16 v[0:15], v[0:3], v[142:145], 0
	ds_read_b128 v[146:149], v106 offset:32
	ds_read_b128 v[150:153], v107 offset:32
	s_waitcnt lgkmcnt(0)
	v_mfma_f32_32x32x16_bf16 v[0:15], v[146:149], v[150:153], v[0:15]
	ds_read_b128 v[146:149], v106 offset:64
	ds_read_b128 v[154:157], v107 offset:64
	s_waitcnt lgkmcnt(0)
	v_mfma_f32_32x32x16_bf16 v[0:15], v[146:149], v[154:157], v[0:15]
	ds_read_b128 v[146:149], v106 offset:96
	ds_read_b128 v[158:161], v107 offset:96
	s_waitcnt lgkmcnt(0)
	v_mfma_f32_32x32x16_bf16 v[0:15], v[146:149], v[158:161], v[0:15]
	ds_read_b128 v[146:149], v108 offset:33792
	s_waitcnt vmcnt(7) lgkmcnt(0)
	v_mfma_f32_32x32x16_bf16 v[0:15], v[146:149], v[50:53], v[0:15]
	ds_read_b128 v[50:53], v108 offset:33824
	s_waitcnt vmcnt(6) lgkmcnt(0)
	v_mfma_f32_32x32x16_bf16 v[0:15], v[50:53], v[114:117], v[0:15]
	ds_read_b128 v[50:53], v108 offset:33856
	s_waitcnt vmcnt(5) lgkmcnt(0)
	v_mfma_f32_32x32x16_bf16 v[0:15], v[50:53], v[118:121], v[0:15]
	ds_read_b128 v[50:53], v108 offset:33888
	s_waitcnt vmcnt(4) lgkmcnt(0)
	v_mfma_f32_32x32x16_bf16 v[0:15], v[50:53], v[122:125], v[0:15]
	ds_read_b128 v[50:53], v106 offset:9216
	s_waitcnt lgkmcnt(0)
	v_mfma_f32_32x32x16_bf16 v[0:15], v[50:53], v[142:145], v[0:15]
	ds_read_b128 v[50:53], v106 offset:9248
	s_waitcnt lgkmcnt(0)
	v_mfma_f32_32x32x16_bf16 v[0:15], v[50:53], v[150:153], v[0:15]
	ds_read_b128 v[50:53], v106 offset:9280
	s_waitcnt lgkmcnt(0)
	v_mfma_f32_32x32x16_bf16 v[0:15], v[50:53], v[154:157], v[0:15]
	ds_read_b128 v[50:53], v106 offset:9312
	s_waitcnt lgkmcnt(0)
	v_mfma_f32_32x32x16_bf16 v[0:15], v[50:53], v[158:161], v[0:15]
	ds_read_b128 v[50:53], v108 offset:43008
	s_waitcnt vmcnt(3) lgkmcnt(0)
	v_mfma_f32_32x32x16_bf16 v[0:15], v[50:53], v[126:129], v[0:15]
	ds_read_b128 v[50:53], v108 offset:43040
	s_waitcnt vmcnt(2) lgkmcnt(0)
	v_mfma_f32_32x32x16_bf16 v[0:15], v[50:53], v[130:133], v[0:15]
	ds_read_b128 v[50:53], v108 offset:43072
	s_waitcnt vmcnt(1) lgkmcnt(0)
	v_mfma_f32_32x32x16_bf16 v[0:15], v[50:53], v[134:137], v[0:15]
	ds_read_b128 v[50:53], v108 offset:43104
	s_waitcnt vmcnt(0) lgkmcnt(0)
	v_mfma_f32_32x32x16_bf16 v[0:15], v[50:53], v[138:141], v[0:15]
	s_nop 11
	ds_write2_b32 v109, v0, v1 offset1:132
	v_add_u32_e32 v0, 0x400, v109
	ds_write2_b32 v0, v2, v3 offset0:8 offset1:140
	v_add_u32_e32 v0, 0x1000, v109
	ds_write2_b32 v0, v4, v5 offset0:32 offset1:164
	v_add_u32_e32 v0, 0x1400, v109
	ds_write2_b32 v0, v6, v7 offset0:40 offset1:172
	v_add_u32_e32 v0, 0x2000, v109
	ds_write2_b32 v0, v8, v9 offset0:64 offset1:196
	v_add_u32_e32 v0, 0x2400, v109
	ds_write2_b32 v0, v10, v11 offset0:72 offset1:204
	v_add_u32_e32 v0, 0x3000, v109
	ds_write2_b32 v0, v12, v13 offset0:96 offset1:228
	v_add_u32_e32 v0, 0x3400, v109
	ds_write2_b32 v0, v14, v15 offset0:104 offset1:236
	s_waitcnt lgkmcnt(0)
	s_barrier
; DI unsigned cvtpk(float lo, float hi) { f32x2_t v = {lo, hi}; bf16x2_t b = __builtin_convertvector(v, bf16x2_t); return __builtin_bit_cast(unsigned, b); }
; DI float bflo(unsigned u) { return __uint_as_float(u << 16); }
; DI float bfhi(unsigned u) { return __uint_as_float(u & 0xffff0000u); }
; DI float shx(float v, int mask, int lane) { return __int_as_float(__builtin_amdgcn_ds_bpermute((lane ^ mask) << 2, __float_as_int(v))); }
; DI float silu_f(float x) { return x * sigm_f(x); }
; DI void phase_gla3(ArgsP a, int tb_, int l, bool with_ctx, char* shm, int vcu, int G) {
;     ...
;             { const int i = j, vg = kg; float o[16]; float ss = 0.f;
; #pragma unroll
;               for (int q = 0; q < 4; ++q) { const f32x4 t4 = *(const f32x4*)(OS + i * 132 + vg * 16 + 4 * q); o[4 * q] = t4.x; o[4 * q + 1] = t4.y; o[4 * q + 2] = t4.z; o[4 * q + 3] = t4.w; ss += (t4.x * t4.x + t4.y * t4.y) + (t4.z * t4.z + t4.w * t4.w); }
;               ss += shx(ss, 1, lane); ss += shx(ss, 2, lane); ss += shx(ss, 4, lane);
;               const float rn = rsqrtf(ss * (1.f / 128.f) + EPS);
;               const float gr[16] = {bflo(r0.x), bfhi(r0.x), bflo(r0.y), bfhi(r0.y), bflo(r0.z), bfhi(r0.z), bflo(r0.w), bfhi(r0.w), bflo(r1.x), bfhi(r1.x), bflo(r1.y), bfhi(r1.y), bflo(r1.z), bfhi(r1.z), bflo(r1.w), bfhi(r1.w)};
;               float y[16];
; #pragma unroll
;               for (int q = 0; q < 16; ++q) y[q] = o[q] * rn * ggl[vg * 16 + q] * silu_f(gr[q]);
;               u32x4 w0, w1; w0.x = cvtpk(y[0], y[1]); w0.y = cvtpk(y[2], y[3]); w0.z = cvtpk(y[4], y[5]); w0.w = cvtpk(y[6], y[7]); w1.x = cvtpk(y[8], y[9]); w1.y = cvtpk(y[10], y[11]); w1.z = cvtpk(y[12], y[13]); w1.w = cvtpk(y[14], y[15]);
;               u32x4* op = (u32x4*)(og + (size_t)(m0 + i) * 512 + h * 128 + vg * 16); op[0] = w0; op[1] = w1; }
;             __syncthreads();
	ds_read_b128 v[4:7], v110
	ds_read_b128 v[12:15], v110 offset:16
	ds_read_b128 v[50:53], v110 offset:32
	ds_read_b128 v[114:117], v110 offset:48
	s_waitcnt lgkmcnt(3)
	v_pk_mul_f32 v[54:55], v[6:7], v[6:7]
	v_pk_mul_f32 v[118:119], v[4:5], v[4:5]
	s_waitcnt lgkmcnt(0)
	v_mul_f32_e32 v49, v114, v114
	v_pk_mov_b32 v[120:121], v[118:119], v[54:55] op_sel:[1,0]
	v_mov_b32_e32 v119, v55
	v_pk_add_f32 v[54:55], v[120:121], v[118:119]
	v_pk_mul_f32 v[118:119], v[14:15], v[14:15]
	v_pk_mul_f32 v[120:121], v[12:13], v[12:13]
	v_mul_f32_e32 v79, v115, v115
	v_pk_mov_b32 v[122:123], v[120:121], v[118:119] op_sel:[1,0]
	v_mov_b32_e32 v121, v119
	v_pk_add_f32 v[118:119], v[122:123], v[120:121]
	v_pk_add_f32 v[54:55], v[54:55], v[54:55] op_sel:[0,1] op_sel_hi:[1,0]
	v_pk_add_f32 v[118:119], v[118:119], v[118:119] op_sel:[0,1] op_sel_hi:[1,0]
	v_mov_b32_e32 v55, v49
	v_mov_b32_e32 v119, v79
	v_pk_add_f32 v[54:55], v[54:55], v[118:119]
	v_mul_f32_e32 v118, v51, v51
	v_mul_f32_e32 v120, v53, v53
	v_mul_f32_e32 v81, v116, v116
	v_mul_f32_e32 v122, v117, v117
	v_pk_fma_f32 v[118:119], v[50:51], v[50:51], v[118:119] op_sel_hi:[1,1,0]
	v_pk_fma_f32 v[120:121], v[52:53], v[52:53], v[120:121] op_sel_hi:[1,1,0]
	v_mov_b32_e32 v119, v81
	v_mov_b32_e32 v121, v122
	v_pk_add_f32 v[118:119], v[118:119], v[120:121]
	v_pk_add_f32 v[54:55], v[54:55], v[118:119]
	v_add_f32_e32 v49, v54, v55
	s_waitcnt lgkmcnt(0)
	s_nop 1
	v_add_f32_dpp v49, v49, v49 quad_perm:[1,0,3,2] row_mask:0xf bank_mask:0xf
	s_waitcnt lgkmcnt(0)
	s_nop 1
	v_add_f32_dpp v54, v49, v49 quad_perm:[2,3,0,1] row_mask:0xf bank_mask:0xf
	v_ashrrev_i32_e32 v49, 31, v48
	s_waitcnt lgkmcnt(0)
	s_nop 1
	v_add_f32_dpp v54, v54, v54 row_half_mirror row_mask:0xf bank_mask:0xf
	v_fmamk_f32 v54, v54, 0x3c000000, v230
	v_mul_f32_e32 v55, 0x4b800000, v54
	v_cmp_gt_f32_e32 vcc, s76, v54
	s_nop 1
	v_cndmask_b32_e32 v54, v54, v55, vcc
	v_rsq_f32_e32 v55, v54
	v_lshlrev_b32_e32 v54, 16, v44
	v_mul_f32_e32 v79, 0xbfb8aa3b, v54
	v_exp_f32_e32 v79, v79
	v_mul_f32_e32 v81, 0x45800000, v55
	v_cndmask_b32_e32 v126, v55, v81, vcc
	v_and_b32_e32 v55, 0xffff0000, v44
	v_add_f32_e32 v44, 1.0, v79
	v_mul_f32_e32 v79, 0xbfb8aa3b, v55
	v_exp_f32_e32 v79, v79
	v_pk_mul_f32 v[4:5], v[4:5], v[126:127] op_sel_hi:[1,0]
	v_rcp_f32_e32 v128, v44
	v_pk_mul_f32 v[6:7], v[6:7], v[126:127] op_sel_hi:[1,0]
	v_pk_mul_f32 v[12:13], v[12:13], v[126:127] op_sel_hi:[1,0]
	s_and_b64 vcc, exec, s[60:61]
	s_waitcnt vmcnt(3)
	v_pk_mul_f32 v[0:1], v[192:193], v[4:5]
	v_add_f32_e32 v4, 1.0, v79
	v_rcp_f32_e32 v129, v4
	v_lshlrev_b32_e32 v4, 16, v45
	v_mul_f32_e32 v5, 0xbfb8aa3b, v4
	v_exp_f32_e32 v44, v5
	v_and_b32_e32 v5, 0xffff0000, v45
	v_mul_f32_e32 v45, 0xbfb8aa3b, v5
	v_exp_f32_e32 v45, v45
	v_add_f32_e32 v44, 1.0, v44
	v_pk_mul_f32 v[2:3], v[194:195], v[6:7]
	v_rcp_f32_e32 v44, v44
	v_add_f32_e32 v6, 1.0, v45
	v_rcp_f32_e32 v45, v6
	v_lshlrev_b32_e32 v6, 16, v46
	v_pk_mul_f32 v[54:55], v[128:129], v[54:55]
	v_mul_f32_e32 v7, 0xbfb8aa3b, v6
	v_pk_mul_f32 v[0:1], v[54:55], v[0:1]
	v_exp_f32_e32 v54, v7
	v_pk_mul_f32 v[4:5], v[44:45], v[4:5]
	v_and_b32_e32 v7, 0xffff0000, v46
	v_pk_mul_f32 v[2:3], v[4:5], v[2:3]
	v_mul_f32_e32 v5, 0xbfb8aa3b, v7
	v_exp_f32_e32 v5, v5
	v_add_f32_e32 v4, 1.0, v54
	v_rcp_f32_e32 v4, v4
	s_waitcnt vmcnt(2)
	v_pk_mul_f32 v[8:9], v[196:197], v[12:13]
	v_add_f32_e32 v5, 1.0, v5
	v_rcp_f32_e32 v5, v5
	v_lshlrev_b32_e32 v12, 16, v47
	v_mul_f32_e32 v13, 0xbfb8aa3b, v12
	v_exp_f32_e32 v44, v13
	v_and_b32_e32 v13, 0xffff0000, v47
	v_pk_mul_f32 v[4:5], v[4:5], v[6:7]
	v_mul_f32_e32 v7, 0xbfb8aa3b, v13
	v_exp_f32_e32 v7, v7
	v_add_f32_e32 v6, 1.0, v44
	v_rcp_f32_e32 v6, v6
	v_pk_mul_f32 v[4:5], v[4:5], v[8:9]
	v_add_f32_e32 v7, 1.0, v7
	v_rcp_f32_e32 v7, v7
	v_pk_mul_f32 v[8:9], v[14:15], v[126:127] op_sel_hi:[1,0]
	v_cvt_pk_bf16_f32 v0, v0, v1
	v_pk_mul_f32 v[8:9], v[198:199], v[8:9]
	v_lshlrev_b32_e32 v10, 16, v40
	v_mul_f32_e32 v11, 0xbfb8aa3b, v10
	v_exp_f32_e32 v14, v11
	v_pk_mul_f32 v[6:7], v[6:7], v[12:13]
	v_and_b32_e32 v11, 0xffff0000, v40
	v_pk_mul_f32 v[6:7], v[6:7], v[8:9]
	v_mul_f32_e32 v9, 0xbfb8aa3b, v11
	v_exp_f32_e32 v9, v9
	v_add_f32_e32 v8, 1.0, v14
	v_rcp_f32_e32 v8, v8
	v_lshlrev_b32_e32 v14, 16, v41
	v_add_f32_e32 v9, 1.0, v9
	v_rcp_f32_e32 v9, v9
	v_mul_f32_e32 v15, 0xbfb8aa3b, v14
	v_exp_f32_e32 v40, v15
	v_and_b32_e32 v15, 0xffff0000, v41
	v_pk_mul_f32 v[8:9], v[8:9], v[10:11]
	v_mul_f32_e32 v11, 0xbfb8aa3b, v15
	v_exp_f32_e32 v11, v11
	v_add_f32_e32 v10, 1.0, v40
	v_lshlrev_b32_e32 v40, 16, v42
	v_and_b32_e32 v41, 0xffff0000, v42
	v_add_f32_e32 v11, 1.0, v11
	v_mul_f32_e32 v42, 0xbfb8aa3b, v40
	v_mul_f32_e32 v44, 0xbfb8aa3b, v41
	v_rcp_f32_e32 v10, v10
	v_rcp_f32_e32 v11, v11
	v_exp_f32_e32 v42, v42
	v_exp_f32_e32 v44, v44
	v_pk_mul_f32 v[12:13], v[50:51], v[126:127] op_sel_hi:[1,0]
	v_pk_mul_f32 v[10:11], v[10:11], v[14:15]
	v_add_f32_e32 v14, 1.0, v42
	v_add_f32_e32 v15, 1.0, v44
	s_waitcnt vmcnt(0)
	v_pk_mul_f32 v[12:13], v[200:201], v[12:13]
	v_rcp_f32_e32 v14, v14
	v_rcp_f32_e32 v15, v15
	v_pk_mul_f32 v[8:9], v[8:9], v[12:13]
	v_pk_mul_f32 v[12:13], v[52:53], v[126:127] op_sel_hi:[1,0]
	v_cvt_pk_bf16_f32 v1, v2, v3
	v_pk_mul_f32 v[12:13], v[202:203], v[12:13]
	v_pk_mul_f32 v[14:15], v[14:15], v[40:41]
	v_pk_mul_f32 v[10:11], v[10:11], v[12:13]
	v_pk_mul_f32 v[12:13], v[114:115], v[126:127] op_sel_hi:[1,0]
	v_cvt_pk_bf16_f32 v2, v4, v5
	v_pk_mul_f32 v[12:13], v[12:13], v[204:205]
	v_cvt_pk_bf16_f32 v4, v8, v9
	v_pk_mul_f32 v[12:13], v[14:15], v[12:13]
	v_lshlrev_b32_e32 v14, 16, v43
	v_mul_f32_e32 v15, 0xbfb8aa3b, v14
	v_exp_f32_e32 v40, v15
	v_and_b32_e32 v15, 0xffff0000, v43
	v_mul_f32_e32 v41, 0xbfb8aa3b, v15
	v_exp_f32_e32 v41, v41
	v_add_f32_e32 v40, 1.0, v40
	v_rcp_f32_e32 v40, v40
	v_pk_mul_f32 v[42:43], v[116:117], v[126:127] op_sel_hi:[1,0]
	v_add_f32_e32 v41, 1.0, v41
	v_rcp_f32_e32 v41, v41
	v_cvt_pk_bf16_f32 v5, v10, v11
	v_pk_mul_f32 v[10:11], v[42:43], v[206:207]
	v_cvt_pk_bf16_f32 v3, v6, v7
	v_pk_mul_f32 v[8:9], v[40:41], v[14:15]
	v_cvt_pk_bf16_f32 v6, v12, v13
	v_pk_mul_f32 v[8:9], v[8:9], v[10:11]
	v_mov_b64_e32 v[54:55], v[22:23]
	v_cvt_pk_bf16_f32 v7, v8, v9
	v_lshlrev_b64 v[8:9], 10, v[48:49]
	v_lshl_add_u64 v[8:9], v[84:85], 0, v[8:9]
	global_store_dwordx4 v[8:9], v[0:3], off
	global_store_dwordx4 v[8:9], v[4:7], off offset:16
	v_mov_b64_e32 v[50:51], v[38:39]
	v_mov_b64_e32 v[0:1], v[24:25]
	v_mov_b64_e32 v[46:47], v[34:35]
	v_mov_b64_e32 v[42:43], v[30:31]
	v_mov_b64_e32 v[2:3], v[26:27]
	v_mov_b64_e32 v[52:53], v[20:21]
	v_mov_b64_e32 v[48:49], v[36:37]
	v_mov_b64_e32 v[44:45], v[32:33]
	v_mov_b64_e32 v[40:41], v[28:29]
	s_barrier
	s_cbranch_vccnz .LBB0_1415
